# th4 plus M-segment framing: redundant post-barrier lgkmcnt(0) and mid-segment setprio flips removed, priority raised before the barrier and lowered after it
# speedup vs baseline: 1.0197x; 1.0056x over previous
.LBB0_255:
	s_ashr_i32 s17, s16, 31
	s_lshl_b64 s[8:9], s[16:17], 20
	v_readlane_b32 s18, v254, 39
	v_readlane_b32 s19, v254, 40
	s_add_u32 s18, s18, s8
	s_addc_u32 s19, s19, s9
	s_and_b64 s[8:9], s[36:37], exec
	s_cselect_b32 s8, s19, s3
	s_cselect_b32 s9, s18, s2
	s_ashr_i32 s15, s14, 31
	s_lshl_b64 s[20:21], s[14:15], 20
	s_add_u32 s20, s29, s20
	s_addc_u32 s21, s38, s21
	s_and_b64 s[26:27], s[36:37], exec
	s_cselect_b32 s15, s21, s23
	s_cselect_b32 s17, s20, s22
	s_add_u32 s2, s2, 0x80800
	s_addc_u32 s3, s3, 0
	s_add_u32 s33, s22, 0x100
	s_addc_u32 s34, s23, 0
	s_mov_b32 s35, -2
	s_add_u32 s22, s2, 0xfff80800
	s_addc_u32 s23, s3, -1
	s_add_i32 s48, 0, 0x10000
	s_cmp_eq_u32 s35, 28
	s_cselect_b32 s27, s8, s23
	s_cselect_b32 s26, s9, s22
	s_cselect_b32 s23, s15, s34
	s_cselect_b32 s22, s17, s33
	s_add_i32 s50, 0, 0x14000
	v_add_u32_e32 v176, s48, v191
	v_add_u32_e32 v188, s50, v191
	ds_read_b128 v[148:151], v176
	ds_read_b128 v[152:155], v176 offset:1024
	ds_read_b128 v[172:175], v176 offset:2048
	ds_read_b128 v[176:179], v176 offset:3072
	ds_read_b128 v[180:183], v188
	ds_read_b128 v[184:187], v188 offset:1024
	ds_read_b128 v[196:199], v188 offset:2048
	ds_read_b128 v[200:203], v188 offset:3072
	s_add_i32 m0, s39, 0xc000
	ds_read_b128 v[204:207], v194
	ds_read_b128 v[212:215], v194 offset:1024
	ds_read_b128 v[216:219], v194 offset:2048
	ds_read_b128 v[220:223], v194 offset:3072
	ds_read_b128 v[224:227], v194 offset:4096
	ds_read_b128 v[228:231], v194 offset:5120
	ds_read_b128 v[232:235], v194 offset:6144
	ds_read_b128 v[236:239], v194 offset:7168
	global_load_lds_dwordx4 v168, s[2:3]
	s_add_i32 m0, s39, 0xe000
	s_nop 0
	global_load_lds_dwordx4 v170, s[2:3]
	s_waitcnt vmcnt(8)
	s_waitcnt lgkmcnt(0)
	s_setprio 1
	s_barrier
	v_mfma_f32_16x16x32_bf16 v[144:147], v[148:151], v[204:207], 0
	v_mfma_f32_16x16x32_bf16 v[136:139], v[172:175], v[204:207], 0
	v_mfma_f32_16x16x32_bf16 v[128:131], v[148:151], v[216:219], 0
	v_mfma_f32_16x16x32_bf16 v[120:123], v[172:175], v[216:219], 0
	v_mfma_f32_16x16x32_bf16 v[112:115], v[148:151], v[224:227], 0
	v_mfma_f32_16x16x32_bf16 v[104:107], v[172:175], v[224:227], 0
	v_mfma_f32_16x16x32_bf16 v[96:99], v[148:151], v[232:235], 0
	v_mfma_f32_16x16x32_bf16 v[88:91], v[172:175], v[232:235], 0
	v_mfma_f32_16x16x32_bf16 v[144:147], v[152:155], v[212:215], v[144:147]
	v_mfma_f32_16x16x32_bf16 v[136:139], v[176:179], v[212:215], v[136:139]
	v_mfma_f32_16x16x32_bf16 v[128:131], v[152:155], v[220:223], v[128:131]
	v_mfma_f32_16x16x32_bf16 v[120:123], v[176:179], v[220:223], v[120:123]
	v_mfma_f32_16x16x32_bf16 v[112:115], v[152:155], v[228:231], v[112:115]
	v_mfma_f32_16x16x32_bf16 v[104:107], v[176:179], v[228:231], v[104:107]
	v_mfma_f32_16x16x32_bf16 v[96:99], v[152:155], v[236:239], v[96:99]
	v_mfma_f32_16x16x32_bf16 v[88:91], v[176:179], v[236:239], v[88:91]
	v_mfma_f32_16x16x32_bf16 v[140:143], v[180:183], v[204:207], 0
	v_mfma_f32_16x16x32_bf16 v[132:135], v[196:199], v[204:207], 0
	v_mfma_f32_16x16x32_bf16 v[124:127], v[180:183], v[216:219], 0
	v_mfma_f32_16x16x32_bf16 v[116:119], v[196:199], v[216:219], 0
	v_mfma_f32_16x16x32_bf16 v[108:111], v[180:183], v[224:227], 0
	v_mfma_f32_16x16x32_bf16 v[100:103], v[196:199], v[224:227], 0
	v_mfma_f32_16x16x32_bf16 v[92:95], v[180:183], v[232:235], 0
	v_mfma_f32_16x16x32_bf16 v[84:87], v[196:199], v[232:235], 0
	v_mfma_f32_16x16x32_bf16 v[140:143], v[184:187], v[212:215], v[140:143]
	v_mfma_f32_16x16x32_bf16 v[132:135], v[200:203], v[212:215], v[132:135]
	v_mfma_f32_16x16x32_bf16 v[124:127], v[184:187], v[220:223], v[124:127]
	v_mfma_f32_16x16x32_bf16 v[116:119], v[200:203], v[220:223], v[116:119]
	v_mfma_f32_16x16x32_bf16 v[108:111], v[184:187], v[228:231], v[108:111]
	v_mfma_f32_16x16x32_bf16 v[100:103], v[200:203], v[228:231], v[100:103]
	v_mfma_f32_16x16x32_bf16 v[92:95], v[184:187], v[236:239], v[92:95]
	v_mfma_f32_16x16x32_bf16 v[84:87], v[200:203], v[236:239], v[84:87]
	s_barrier
	s_setprio 0
	s_add_i32 s48, s48, s28
	s_add_u32 s98, s22, 0x80
	s_addc_u32 s99, s23, 0
	s_add_u32 s100, s26, 0x800
	s_addc_u32 s101, s27, 0
	s_mov_b32 m0, s48
	ds_read_b128 v[204:207], v194 offset:16384
	ds_read_b128 v[212:215], v194 offset:17408
	ds_read_b128 v[216:219], v194 offset:18432
	ds_read_b128 v[220:223], v194 offset:19456
	ds_read_b128 v[224:227], v194 offset:20480
	ds_read_b128 v[228:231], v194 offset:21504
	ds_read_b128 v[232:235], v194 offset:22528
	ds_read_b128 v[236:239], v194 offset:23552
	global_load_lds_dwordx4 v2, s[22:23]
	s_add_i32 m0, s48, 0x2000
	s_add_u32 s48, s22, 0x80000
	s_addc_u32 s49, s23, 0
	s_add_i32 s50, s50, s28
	global_load_lds_dwordx4 v156, s[22:23]
	s_mov_b32 m0, s50
	s_nop 0
	global_load_lds_dwordx4 v2, s[48:49]
	s_add_i32 m0, s50, 0x2000
	s_nop 0
	global_load_lds_dwordx4 v156, s[48:49]
	s_mov_b32 m0, s39
	s_nop 0
	global_load_lds_dwordx4 v160, s[26:27]
	s_mov_b32 m0, s41
	s_nop 0
	global_load_lds_dwordx4 v158, s[26:27]
	s_waitcnt vmcnt(8)
	s_waitcnt lgkmcnt(0)
	s_setprio 1
	s_barrier
	v_mfma_f32_16x16x32_bf16 v[80:83], v[148:151], v[204:207], 0
	v_mfma_f32_16x16x32_bf16 v[72:75], v[172:175], v[204:207], 0
	v_mfma_f32_16x16x32_bf16 v[64:67], v[148:151], v[216:219], 0
	v_mfma_f32_16x16x32_bf16 v[56:59], v[172:175], v[216:219], 0
	v_mfma_f32_16x16x32_bf16 v[48:51], v[148:151], v[224:227], 0
	v_mfma_f32_16x16x32_bf16 v[40:43], v[172:175], v[224:227], 0
	v_mfma_f32_16x16x32_bf16 v[32:35], v[148:151], v[232:235], 0
	v_mfma_f32_16x16x32_bf16 v[24:27], v[172:175], v[232:235], 0
	v_mfma_f32_16x16x32_bf16 v[80:83], v[152:155], v[212:215], v[80:83]
	v_mfma_f32_16x16x32_bf16 v[72:75], v[176:179], v[212:215], v[72:75]
	v_mfma_f32_16x16x32_bf16 v[64:67], v[152:155], v[220:223], v[64:67]
	v_mfma_f32_16x16x32_bf16 v[56:59], v[176:179], v[220:223], v[56:59]
	v_mfma_f32_16x16x32_bf16 v[48:51], v[152:155], v[228:231], v[48:51]
	v_mfma_f32_16x16x32_bf16 v[40:43], v[176:179], v[228:231], v[40:43]
	v_mfma_f32_16x16x32_bf16 v[32:35], v[152:155], v[236:239], v[32:35]
	v_mfma_f32_16x16x32_bf16 v[24:27], v[176:179], v[236:239], v[24:27]
	v_mfma_f32_16x16x32_bf16 v[76:79], v[180:183], v[204:207], 0
	v_mfma_f32_16x16x32_bf16 v[68:71], v[196:199], v[204:207], 0
	v_mfma_f32_16x16x32_bf16 v[60:63], v[180:183], v[216:219], 0
	v_mfma_f32_16x16x32_bf16 v[52:55], v[196:199], v[216:219], 0
	v_mfma_f32_16x16x32_bf16 v[44:47], v[180:183], v[224:227], 0
	v_mfma_f32_16x16x32_bf16 v[36:39], v[196:199], v[224:227], 0
	v_mfma_f32_16x16x32_bf16 v[28:31], v[180:183], v[232:235], 0
	v_mfma_f32_16x16x32_bf16 v[20:23], v[196:199], v[232:235], 0
	v_mfma_f32_16x16x32_bf16 v[76:79], v[184:187], v[212:215], v[76:79]
	v_mfma_f32_16x16x32_bf16 v[68:71], v[200:203], v[212:215], v[68:71]
	v_mfma_f32_16x16x32_bf16 v[60:63], v[184:187], v[220:223], v[60:63]
	v_mfma_f32_16x16x32_bf16 v[52:55], v[200:203], v[220:223], v[52:55]
	v_mfma_f32_16x16x32_bf16 v[44:47], v[184:187], v[228:231], v[44:47]
	v_mfma_f32_16x16x32_bf16 v[36:39], v[200:203], v[228:231], v[36:39]
	v_mfma_f32_16x16x32_bf16 v[28:31], v[184:187], v[236:239], v[28:31]
	v_mfma_f32_16x16x32_bf16 v[20:23], v[200:203], v[236:239], v[20:23]
	s_barrier
	s_setprio 0
	s_add_i32 s48, 0, 0x18000
	s_add_i32 s49, 0, 0x1c000
	v_add_u32_e32 v176, s48, v191
	v_add_u32_e32 v195, s49, v191
	ds_read_b128 v[148:151], v176
	ds_read_b128 v[152:155], v176 offset:1024
	ds_read_b128 v[172:175], v176 offset:2048
	ds_read_b128 v[176:179], v176 offset:3072
	ds_read_b128 v[180:183], v195
	ds_read_b128 v[184:187], v195 offset:1024
	ds_read_b128 v[196:199], v195 offset:2048
	ds_read_b128 v[200:203], v195 offset:3072
	s_add_u32 s26, s26, 0x80000
	s_addc_u32 s27, s27, 0
	s_mov_b32 m0, s42
	ds_read_b128 v[204:207], v194 offset:32768
	ds_read_b128 v[212:215], v194 offset:33792
	ds_read_b128 v[216:219], v194 offset:34816
	ds_read_b128 v[220:223], v194 offset:35840
	ds_read_b128 v[224:227], v194 offset:36864
	ds_read_b128 v[228:231], v194 offset:37888
	ds_read_b128 v[232:235], v194 offset:38912
	ds_read_b128 v[236:239], v194 offset:39936
	global_load_lds_dwordx4 v160, s[26:27]
	s_mov_b32 m0, s43
	s_nop 0
	global_load_lds_dwordx4 v158, s[26:27]
	s_waitcnt vmcnt(8)
	s_waitcnt lgkmcnt(0)
	s_setprio 1
	s_barrier
	v_mfma_f32_16x16x32_bf16 v[144:147], v[148:151], v[204:207], v[144:147]
	v_mfma_f32_16x16x32_bf16 v[136:139], v[172:175], v[204:207], v[136:139]
	v_mfma_f32_16x16x32_bf16 v[128:131], v[148:151], v[216:219], v[128:131]
	v_mfma_f32_16x16x32_bf16 v[120:123], v[172:175], v[216:219], v[120:123]
	v_mfma_f32_16x16x32_bf16 v[112:115], v[148:151], v[224:227], v[112:115]
	v_mfma_f32_16x16x32_bf16 v[104:107], v[172:175], v[224:227], v[104:107]
	v_mfma_f32_16x16x32_bf16 v[96:99], v[148:151], v[232:235], v[96:99]
	v_mfma_f32_16x16x32_bf16 v[88:91], v[172:175], v[232:235], v[88:91]
	v_mfma_f32_16x16x32_bf16 v[144:147], v[152:155], v[212:215], v[144:147]
	v_mfma_f32_16x16x32_bf16 v[136:139], v[176:179], v[212:215], v[136:139]
	v_mfma_f32_16x16x32_bf16 v[128:131], v[152:155], v[220:223], v[128:131]
	v_mfma_f32_16x16x32_bf16 v[120:123], v[176:179], v[220:223], v[120:123]
	v_mfma_f32_16x16x32_bf16 v[112:115], v[152:155], v[228:231], v[112:115]
	v_mfma_f32_16x16x32_bf16 v[104:107], v[176:179], v[228:231], v[104:107]
	v_mfma_f32_16x16x32_bf16 v[96:99], v[152:155], v[236:239], v[96:99]
	v_mfma_f32_16x16x32_bf16 v[88:91], v[176:179], v[236:239], v[88:91]
	v_mfma_f32_16x16x32_bf16 v[140:143], v[180:183], v[204:207], v[140:143]
	v_mfma_f32_16x16x32_bf16 v[132:135], v[196:199], v[204:207], v[132:135]
	v_mfma_f32_16x16x32_bf16 v[124:127], v[180:183], v[216:219], v[124:127]
	v_mfma_f32_16x16x32_bf16 v[116:119], v[196:199], v[216:219], v[116:119]
	v_mfma_f32_16x16x32_bf16 v[108:111], v[180:183], v[224:227], v[108:111]
	v_mfma_f32_16x16x32_bf16 v[100:103], v[196:199], v[224:227], v[100:103]
	v_mfma_f32_16x16x32_bf16 v[92:95], v[180:183], v[232:235], v[92:95]
	v_mfma_f32_16x16x32_bf16 v[84:87], v[196:199], v[232:235], v[84:87]
	v_mfma_f32_16x16x32_bf16 v[140:143], v[184:187], v[212:215], v[140:143]
	v_mfma_f32_16x16x32_bf16 v[132:135], v[200:203], v[212:215], v[132:135]
	v_mfma_f32_16x16x32_bf16 v[124:127], v[184:187], v[220:223], v[124:127]
	v_mfma_f32_16x16x32_bf16 v[116:119], v[200:203], v[220:223], v[116:119]
	v_mfma_f32_16x16x32_bf16 v[108:111], v[184:187], v[228:231], v[108:111]
	v_mfma_f32_16x16x32_bf16 v[100:103], v[200:203], v[228:231], v[100:103]
	v_mfma_f32_16x16x32_bf16 v[92:95], v[184:187], v[236:239], v[92:95]
	v_mfma_f32_16x16x32_bf16 v[84:87], v[200:203], v[236:239], v[84:87]
	s_barrier
	s_setprio 0
	s_add_i32 s26, s48, s28
	s_mov_b32 m0, s26
	ds_read_b128 v[204:207], v194 offset:49152
	ds_read_b128 v[212:215], v194 offset:50176
	ds_read_b128 v[216:219], v194 offset:51200
	ds_read_b128 v[220:223], v194 offset:52224
	ds_read_b128 v[224:227], v194 offset:53248
	ds_read_b128 v[228:231], v194 offset:54272
	ds_read_b128 v[232:235], v194 offset:55296
	ds_read_b128 v[236:239], v194 offset:56320
	global_load_lds_dwordx4 v2, s[98:99]
	s_add_i32 m0, s26, 0x2000
	s_add_u32 s22, s22, 0x80080
	s_addc_u32 s23, s23, 0
	s_add_i32 s26, s49, s28
	global_load_lds_dwordx4 v156, s[98:99]
	s_mov_b32 m0, s26
	s_nop 0
	global_load_lds_dwordx4 v2, s[22:23]
	s_add_i32 m0, s26, 0x2000
	s_nop 0
	global_load_lds_dwordx4 v156, s[22:23]
	s_mov_b32 m0, s44
	s_nop 0
	global_load_lds_dwordx4 v160, s[100:101]
	s_mov_b32 m0, s45
	s_nop 0
	global_load_lds_dwordx4 v158, s[100:101]
	s_waitcnt vmcnt(8)
	s_waitcnt lgkmcnt(0)
	s_setprio 1
	s_barrier
	v_mfma_f32_16x16x32_bf16 v[80:83], v[148:151], v[204:207], v[80:83]
	v_mfma_f32_16x16x32_bf16 v[72:75], v[172:175], v[204:207], v[72:75]
	v_mfma_f32_16x16x32_bf16 v[64:67], v[148:151], v[216:219], v[64:67]
	v_mfma_f32_16x16x32_bf16 v[56:59], v[172:175], v[216:219], v[56:59]
	v_mfma_f32_16x16x32_bf16 v[48:51], v[148:151], v[224:227], v[48:51]
	v_mfma_f32_16x16x32_bf16 v[40:43], v[172:175], v[224:227], v[40:43]
	v_mfma_f32_16x16x32_bf16 v[32:35], v[148:151], v[232:235], v[32:35]
	v_mfma_f32_16x16x32_bf16 v[24:27], v[172:175], v[232:235], v[24:27]
	v_mfma_f32_16x16x32_bf16 v[80:83], v[152:155], v[212:215], v[80:83]
	v_mfma_f32_16x16x32_bf16 v[72:75], v[176:179], v[212:215], v[72:75]
	v_mfma_f32_16x16x32_bf16 v[64:67], v[152:155], v[220:223], v[64:67]
	v_mfma_f32_16x16x32_bf16 v[56:59], v[176:179], v[220:223], v[56:59]
	v_mfma_f32_16x16x32_bf16 v[48:51], v[152:155], v[228:231], v[48:51]
	v_mfma_f32_16x16x32_bf16 v[40:43], v[176:179], v[228:231], v[40:43]
	v_mfma_f32_16x16x32_bf16 v[32:35], v[152:155], v[236:239], v[32:35]
	v_mfma_f32_16x16x32_bf16 v[24:27], v[176:179], v[236:239], v[24:27]
	v_mfma_f32_16x16x32_bf16 v[76:79], v[180:183], v[204:207], v[76:79]
	v_mfma_f32_16x16x32_bf16 v[68:71], v[196:199], v[204:207], v[68:71]
	v_mfma_f32_16x16x32_bf16 v[60:63], v[180:183], v[216:219], v[60:63]
	v_mfma_f32_16x16x32_bf16 v[52:55], v[196:199], v[216:219], v[52:55]
	v_mfma_f32_16x16x32_bf16 v[44:47], v[180:183], v[224:227], v[44:47]
	v_mfma_f32_16x16x32_bf16 v[36:39], v[196:199], v[224:227], v[36:39]
	v_mfma_f32_16x16x32_bf16 v[28:31], v[180:183], v[232:235], v[28:31]
	v_mfma_f32_16x16x32_bf16 v[20:23], v[196:199], v[232:235], v[20:23]
	v_mfma_f32_16x16x32_bf16 v[76:79], v[184:187], v[212:215], v[76:79]
	v_mfma_f32_16x16x32_bf16 v[68:71], v[200:203], v[212:215], v[68:71]
	v_mfma_f32_16x16x32_bf16 v[60:63], v[184:187], v[220:223], v[60:63]
	v_mfma_f32_16x16x32_bf16 v[52:55], v[200:203], v[220:223], v[52:55]
	v_mfma_f32_16x16x32_bf16 v[44:47], v[184:187], v[228:231], v[44:47]
	v_mfma_f32_16x16x32_bf16 v[36:39], v[200:203], v[228:231], v[36:39]
	v_mfma_f32_16x16x32_bf16 v[28:31], v[184:187], v[236:239], v[28:31]
	v_mfma_f32_16x16x32_bf16 v[20:23], v[200:203], v[236:239], v[20:23]
	s_barrier
	s_setprio 0
	s_add_i32 s35, s35, 2
	s_add_u32 s2, s2, 0x1000
	s_addc_u32 s3, s3, 0
	s_add_u32 s33, s33, 0x100
	s_addc_u32 s34, s34, 0
	s_cmp_gt_u32 s35, 29
	s_cbranch_scc0 .LBB0_256
	s_branch .Lpeel_done_256
.LBB0_256:
	s_add_u32 s22, s2, 0xfff80800
	s_addc_u32 s23, s3, -1
	s_add_i32 s48, 0, 0x10000
	s_cmp_eq_u32 s35, 28
	s_cselect_b32 s27, s8, s23
	s_cselect_b32 s26, s9, s22
	s_cselect_b32 s23, s15, s34
	s_cselect_b32 s22, s17, s33
	s_add_i32 s50, 0, 0x14000
	v_add_u32_e32 v176, s48, v191
	v_add_u32_e32 v188, s50, v191
	ds_read_b128 v[148:151], v176
	ds_read_b128 v[152:155], v176 offset:1024
	ds_read_b128 v[172:175], v176 offset:2048
	ds_read_b128 v[176:179], v176 offset:3072
	ds_read_b128 v[180:183], v188
	ds_read_b128 v[184:187], v188 offset:1024
	ds_read_b128 v[196:199], v188 offset:2048
	ds_read_b128 v[200:203], v188 offset:3072
	s_add_i32 m0, s39, 0xc000
	ds_read_b128 v[204:207], v194
	ds_read_b128 v[212:215], v194 offset:1024
	ds_read_b128 v[216:219], v194 offset:2048
	ds_read_b128 v[220:223], v194 offset:3072
	ds_read_b128 v[224:227], v194 offset:4096
	ds_read_b128 v[228:231], v194 offset:5120
	ds_read_b128 v[232:235], v194 offset:6144
	ds_read_b128 v[236:239], v194 offset:7168
	global_load_lds_dwordx4 v168, s[2:3]
	s_add_i32 m0, s39, 0xe000
	s_nop 0
	global_load_lds_dwordx4 v170, s[2:3]
	s_waitcnt vmcnt(8)
	s_waitcnt lgkmcnt(0)
	s_setprio 1
	s_barrier
	v_mfma_f32_16x16x32_bf16 v[144:147], v[148:151], v[204:207], v[144:147]
	v_mfma_f32_16x16x32_bf16 v[136:139], v[172:175], v[204:207], v[136:139]
	v_mfma_f32_16x16x32_bf16 v[128:131], v[148:151], v[216:219], v[128:131]
	v_mfma_f32_16x16x32_bf16 v[120:123], v[172:175], v[216:219], v[120:123]
	v_mfma_f32_16x16x32_bf16 v[112:115], v[148:151], v[224:227], v[112:115]
	v_mfma_f32_16x16x32_bf16 v[104:107], v[172:175], v[224:227], v[104:107]
	v_mfma_f32_16x16x32_bf16 v[96:99], v[148:151], v[232:235], v[96:99]
	v_mfma_f32_16x16x32_bf16 v[88:91], v[172:175], v[232:235], v[88:91]
	v_mfma_f32_16x16x32_bf16 v[144:147], v[152:155], v[212:215], v[144:147]
	v_mfma_f32_16x16x32_bf16 v[136:139], v[176:179], v[212:215], v[136:139]
	v_mfma_f32_16x16x32_bf16 v[128:131], v[152:155], v[220:223], v[128:131]
	v_mfma_f32_16x16x32_bf16 v[120:123], v[176:179], v[220:223], v[120:123]
	v_mfma_f32_16x16x32_bf16 v[112:115], v[152:155], v[228:231], v[112:115]
	v_mfma_f32_16x16x32_bf16 v[104:107], v[176:179], v[228:231], v[104:107]
	v_mfma_f32_16x16x32_bf16 v[96:99], v[152:155], v[236:239], v[96:99]
	v_mfma_f32_16x16x32_bf16 v[88:91], v[176:179], v[236:239], v[88:91]
	v_mfma_f32_16x16x32_bf16 v[140:143], v[180:183], v[204:207], v[140:143]
	v_mfma_f32_16x16x32_bf16 v[132:135], v[196:199], v[204:207], v[132:135]
	v_mfma_f32_16x16x32_bf16 v[124:127], v[180:183], v[216:219], v[124:127]
	v_mfma_f32_16x16x32_bf16 v[116:119], v[196:199], v[216:219], v[116:119]
	v_mfma_f32_16x16x32_bf16 v[108:111], v[180:183], v[224:227], v[108:111]
	v_mfma_f32_16x16x32_bf16 v[100:103], v[196:199], v[224:227], v[100:103]
	v_mfma_f32_16x16x32_bf16 v[92:95], v[180:183], v[232:235], v[92:95]
	v_mfma_f32_16x16x32_bf16 v[84:87], v[196:199], v[232:235], v[84:87]
	v_mfma_f32_16x16x32_bf16 v[140:143], v[184:187], v[212:215], v[140:143]
	v_mfma_f32_16x16x32_bf16 v[132:135], v[200:203], v[212:215], v[132:135]
	v_mfma_f32_16x16x32_bf16 v[124:127], v[184:187], v[220:223], v[124:127]
	v_mfma_f32_16x16x32_bf16 v[116:119], v[200:203], v[220:223], v[116:119]
	v_mfma_f32_16x16x32_bf16 v[108:111], v[184:187], v[228:231], v[108:111]
	v_mfma_f32_16x16x32_bf16 v[100:103], v[200:203], v[228:231], v[100:103]
	v_mfma_f32_16x16x32_bf16 v[92:95], v[184:187], v[236:239], v[92:95]
	v_mfma_f32_16x16x32_bf16 v[84:87], v[200:203], v[236:239], v[84:87]
	s_barrier
	s_setprio 0
	s_add_i32 s48, s48, s28
	s_add_u32 s98, s22, 0x80
	s_addc_u32 s99, s23, 0
	s_add_u32 s100, s26, 0x800
	s_addc_u32 s101, s27, 0
	s_mov_b32 m0, s48
	ds_read_b128 v[204:207], v194 offset:16384
	ds_read_b128 v[212:215], v194 offset:17408
	ds_read_b128 v[216:219], v194 offset:18432
	ds_read_b128 v[220:223], v194 offset:19456
	ds_read_b128 v[224:227], v194 offset:20480
	ds_read_b128 v[228:231], v194 offset:21504
	ds_read_b128 v[232:235], v194 offset:22528
	ds_read_b128 v[236:239], v194 offset:23552
	global_load_lds_dwordx4 v2, s[22:23]
	s_add_i32 m0, s48, 0x2000
	s_add_u32 s48, s22, 0x80000
	s_addc_u32 s49, s23, 0
	s_add_i32 s50, s50, s28
	global_load_lds_dwordx4 v156, s[22:23]
	s_mov_b32 m0, s50
	s_nop 0
	global_load_lds_dwordx4 v2, s[48:49]
	s_add_i32 m0, s50, 0x2000
	s_nop 0
	global_load_lds_dwordx4 v156, s[48:49]
	s_mov_b32 m0, s39
	s_nop 0
	global_load_lds_dwordx4 v160, s[26:27]
	s_mov_b32 m0, s41
	s_nop 0
	global_load_lds_dwordx4 v158, s[26:27]
	s_waitcnt vmcnt(8)
	s_waitcnt lgkmcnt(0)
	s_setprio 1
	s_barrier
	v_mfma_f32_16x16x32_bf16 v[80:83], v[148:151], v[204:207], v[80:83]
	v_mfma_f32_16x16x32_bf16 v[72:75], v[172:175], v[204:207], v[72:75]
	v_mfma_f32_16x16x32_bf16 v[64:67], v[148:151], v[216:219], v[64:67]
	v_mfma_f32_16x16x32_bf16 v[56:59], v[172:175], v[216:219], v[56:59]
	v_mfma_f32_16x16x32_bf16 v[48:51], v[148:151], v[224:227], v[48:51]
	v_mfma_f32_16x16x32_bf16 v[40:43], v[172:175], v[224:227], v[40:43]
	v_mfma_f32_16x16x32_bf16 v[32:35], v[148:151], v[232:235], v[32:35]
	v_mfma_f32_16x16x32_bf16 v[24:27], v[172:175], v[232:235], v[24:27]
	v_mfma_f32_16x16x32_bf16 v[80:83], v[152:155], v[212:215], v[80:83]
	v_mfma_f32_16x16x32_bf16 v[72:75], v[176:179], v[212:215], v[72:75]
	v_mfma_f32_16x16x32_bf16 v[64:67], v[152:155], v[220:223], v[64:67]
	v_mfma_f32_16x16x32_bf16 v[56:59], v[176:179], v[220:223], v[56:59]
	v_mfma_f32_16x16x32_bf16 v[48:51], v[152:155], v[228:231], v[48:51]
	v_mfma_f32_16x16x32_bf16 v[40:43], v[176:179], v[228:231], v[40:43]
	v_mfma_f32_16x16x32_bf16 v[32:35], v[152:155], v[236:239], v[32:35]
	v_mfma_f32_16x16x32_bf16 v[24:27], v[176:179], v[236:239], v[24:27]
	v_mfma_f32_16x16x32_bf16 v[76:79], v[180:183], v[204:207], v[76:79]
	v_mfma_f32_16x16x32_bf16 v[68:71], v[196:199], v[204:207], v[68:71]
	v_mfma_f32_16x16x32_bf16 v[60:63], v[180:183], v[216:219], v[60:63]
	v_mfma_f32_16x16x32_bf16 v[52:55], v[196:199], v[216:219], v[52:55]
	v_mfma_f32_16x16x32_bf16 v[44:47], v[180:183], v[224:227], v[44:47]
	v_mfma_f32_16x16x32_bf16 v[36:39], v[196:199], v[224:227], v[36:39]
	v_mfma_f32_16x16x32_bf16 v[28:31], v[180:183], v[232:235], v[28:31]
	v_mfma_f32_16x16x32_bf16 v[20:23], v[196:199], v[232:235], v[20:23]
	v_mfma_f32_16x16x32_bf16 v[76:79], v[184:187], v[212:215], v[76:79]
	v_mfma_f32_16x16x32_bf16 v[68:71], v[200:203], v[212:215], v[68:71]
	v_mfma_f32_16x16x32_bf16 v[60:63], v[184:187], v[220:223], v[60:63]
	v_mfma_f32_16x16x32_bf16 v[52:55], v[200:203], v[220:223], v[52:55]
	v_mfma_f32_16x16x32_bf16 v[44:47], v[184:187], v[228:231], v[44:47]
	v_mfma_f32_16x16x32_bf16 v[36:39], v[200:203], v[228:231], v[36:39]
	v_mfma_f32_16x16x32_bf16 v[28:31], v[184:187], v[236:239], v[28:31]
	v_mfma_f32_16x16x32_bf16 v[20:23], v[200:203], v[236:239], v[20:23]
	s_barrier
	s_setprio 0
	s_add_i32 s48, 0, 0x18000
	s_add_i32 s49, 0, 0x1c000
	v_add_u32_e32 v176, s48, v191
	v_add_u32_e32 v195, s49, v191
	ds_read_b128 v[148:151], v176
	ds_read_b128 v[152:155], v176 offset:1024
	ds_read_b128 v[172:175], v176 offset:2048
	ds_read_b128 v[176:179], v176 offset:3072
	ds_read_b128 v[180:183], v195
	ds_read_b128 v[184:187], v195 offset:1024
	ds_read_b128 v[196:199], v195 offset:2048
	ds_read_b128 v[200:203], v195 offset:3072
	s_add_u32 s26, s26, 0x80000
	s_addc_u32 s27, s27, 0
	s_mov_b32 m0, s42
	ds_read_b128 v[204:207], v194 offset:32768
	ds_read_b128 v[212:215], v194 offset:33792
	ds_read_b128 v[216:219], v194 offset:34816
	ds_read_b128 v[220:223], v194 offset:35840
	ds_read_b128 v[224:227], v194 offset:36864
	ds_read_b128 v[228:231], v194 offset:37888
	ds_read_b128 v[232:235], v194 offset:38912
	ds_read_b128 v[236:239], v194 offset:39936
	global_load_lds_dwordx4 v160, s[26:27]
	s_mov_b32 m0, s43
	s_nop 0
	global_load_lds_dwordx4 v158, s[26:27]
	s_waitcnt vmcnt(8)
	s_waitcnt lgkmcnt(0)
	s_setprio 1
	s_barrier
	v_mfma_f32_16x16x32_bf16 v[144:147], v[148:151], v[204:207], v[144:147]
	v_mfma_f32_16x16x32_bf16 v[136:139], v[172:175], v[204:207], v[136:139]
	v_mfma_f32_16x16x32_bf16 v[128:131], v[148:151], v[216:219], v[128:131]
	v_mfma_f32_16x16x32_bf16 v[120:123], v[172:175], v[216:219], v[120:123]
	v_mfma_f32_16x16x32_bf16 v[112:115], v[148:151], v[224:227], v[112:115]
	v_mfma_f32_16x16x32_bf16 v[104:107], v[172:175], v[224:227], v[104:107]
	v_mfma_f32_16x16x32_bf16 v[96:99], v[148:151], v[232:235], v[96:99]
	v_mfma_f32_16x16x32_bf16 v[88:91], v[172:175], v[232:235], v[88:91]
	v_mfma_f32_16x16x32_bf16 v[144:147], v[152:155], v[212:215], v[144:147]
	v_mfma_f32_16x16x32_bf16 v[136:139], v[176:179], v[212:215], v[136:139]
	v_mfma_f32_16x16x32_bf16 v[128:131], v[152:155], v[220:223], v[128:131]
	v_mfma_f32_16x16x32_bf16 v[120:123], v[176:179], v[220:223], v[120:123]
	v_mfma_f32_16x16x32_bf16 v[112:115], v[152:155], v[228:231], v[112:115]
	v_mfma_f32_16x16x32_bf16 v[104:107], v[176:179], v[228:231], v[104:107]
	v_mfma_f32_16x16x32_bf16 v[96:99], v[152:155], v[236:239], v[96:99]
	v_mfma_f32_16x16x32_bf16 v[88:91], v[176:179], v[236:239], v[88:91]
	v_mfma_f32_16x16x32_bf16 v[140:143], v[180:183], v[204:207], v[140:143]
	v_mfma_f32_16x16x32_bf16 v[132:135], v[196:199], v[204:207], v[132:135]
	v_mfma_f32_16x16x32_bf16 v[124:127], v[180:183], v[216:219], v[124:127]
	v_mfma_f32_16x16x32_bf16 v[116:119], v[196:199], v[216:219], v[116:119]
	v_mfma_f32_16x16x32_bf16 v[108:111], v[180:183], v[224:227], v[108:111]
	v_mfma_f32_16x16x32_bf16 v[100:103], v[196:199], v[224:227], v[100:103]
	v_mfma_f32_16x16x32_bf16 v[92:95], v[180:183], v[232:235], v[92:95]
	v_mfma_f32_16x16x32_bf16 v[84:87], v[196:199], v[232:235], v[84:87]
	v_mfma_f32_16x16x32_bf16 v[140:143], v[184:187], v[212:215], v[140:143]
	v_mfma_f32_16x16x32_bf16 v[132:135], v[200:203], v[212:215], v[132:135]
	v_mfma_f32_16x16x32_bf16 v[124:127], v[184:187], v[220:223], v[124:127]
	v_mfma_f32_16x16x32_bf16 v[116:119], v[200:203], v[220:223], v[116:119]
	v_mfma_f32_16x16x32_bf16 v[108:111], v[184:187], v[228:231], v[108:111]
	v_mfma_f32_16x16x32_bf16 v[100:103], v[200:203], v[228:231], v[100:103]
	v_mfma_f32_16x16x32_bf16 v[92:95], v[184:187], v[236:239], v[92:95]
	v_mfma_f32_16x16x32_bf16 v[84:87], v[200:203], v[236:239], v[84:87]
	s_barrier
	s_setprio 0
	s_add_i32 s26, s48, s28
	s_mov_b32 m0, s26
	ds_read_b128 v[204:207], v194 offset:49152
	ds_read_b128 v[212:215], v194 offset:50176
	ds_read_b128 v[216:219], v194 offset:51200
	ds_read_b128 v[220:223], v194 offset:52224
	ds_read_b128 v[224:227], v194 offset:53248
	ds_read_b128 v[228:231], v194 offset:54272
	ds_read_b128 v[232:235], v194 offset:55296
	ds_read_b128 v[236:239], v194 offset:56320
	global_load_lds_dwordx4 v2, s[98:99]
	s_add_i32 m0, s26, 0x2000
	s_add_u32 s22, s22, 0x80080
	s_addc_u32 s23, s23, 0
	s_add_i32 s26, s49, s28
	global_load_lds_dwordx4 v156, s[98:99]
	s_mov_b32 m0, s26
	s_nop 0
	global_load_lds_dwordx4 v2, s[22:23]
	s_add_i32 m0, s26, 0x2000
	s_nop 0
	global_load_lds_dwordx4 v156, s[22:23]
	s_mov_b32 m0, s44
	s_nop 0
	global_load_lds_dwordx4 v160, s[100:101]
	s_mov_b32 m0, s45
	s_nop 0
	global_load_lds_dwordx4 v158, s[100:101]
	s_waitcnt vmcnt(8)
	s_waitcnt lgkmcnt(0)
	s_setprio 1
	s_barrier
	v_mfma_f32_16x16x32_bf16 v[80:83], v[148:151], v[204:207], v[80:83]
	v_mfma_f32_16x16x32_bf16 v[72:75], v[172:175], v[204:207], v[72:75]
	v_mfma_f32_16x16x32_bf16 v[64:67], v[148:151], v[216:219], v[64:67]
	v_mfma_f32_16x16x32_bf16 v[56:59], v[172:175], v[216:219], v[56:59]
	v_mfma_f32_16x16x32_bf16 v[48:51], v[148:151], v[224:227], v[48:51]
	v_mfma_f32_16x16x32_bf16 v[40:43], v[172:175], v[224:227], v[40:43]
	v_mfma_f32_16x16x32_bf16 v[32:35], v[148:151], v[232:235], v[32:35]
	v_mfma_f32_16x16x32_bf16 v[24:27], v[172:175], v[232:235], v[24:27]
	v_mfma_f32_16x16x32_bf16 v[80:83], v[152:155], v[212:215], v[80:83]
	v_mfma_f32_16x16x32_bf16 v[72:75], v[176:179], v[212:215], v[72:75]
	v_mfma_f32_16x16x32_bf16 v[64:67], v[152:155], v[220:223], v[64:67]
	v_mfma_f32_16x16x32_bf16 v[56:59], v[176:179], v[220:223], v[56:59]
	v_mfma_f32_16x16x32_bf16 v[48:51], v[152:155], v[228:231], v[48:51]
	v_mfma_f32_16x16x32_bf16 v[40:43], v[176:179], v[228:231], v[40:43]
	v_mfma_f32_16x16x32_bf16 v[32:35], v[152:155], v[236:239], v[32:35]
	v_mfma_f32_16x16x32_bf16 v[24:27], v[176:179], v[236:239], v[24:27]
	v_mfma_f32_16x16x32_bf16 v[76:79], v[180:183], v[204:207], v[76:79]
	v_mfma_f32_16x16x32_bf16 v[68:71], v[196:199], v[204:207], v[68:71]
	v_mfma_f32_16x16x32_bf16 v[60:63], v[180:183], v[216:219], v[60:63]
	v_mfma_f32_16x16x32_bf16 v[52:55], v[196:199], v[216:219], v[52:55]
	v_mfma_f32_16x16x32_bf16 v[44:47], v[180:183], v[224:227], v[44:47]
	v_mfma_f32_16x16x32_bf16 v[36:39], v[196:199], v[224:227], v[36:39]
	v_mfma_f32_16x16x32_bf16 v[28:31], v[180:183], v[232:235], v[28:31]
	v_mfma_f32_16x16x32_bf16 v[20:23], v[196:199], v[232:235], v[20:23]
	v_mfma_f32_16x16x32_bf16 v[76:79], v[184:187], v[212:215], v[76:79]
	v_mfma_f32_16x16x32_bf16 v[68:71], v[200:203], v[212:215], v[68:71]
	v_mfma_f32_16x16x32_bf16 v[60:63], v[184:187], v[220:223], v[60:63]
	v_mfma_f32_16x16x32_bf16 v[52:55], v[200:203], v[220:223], v[52:55]
	v_mfma_f32_16x16x32_bf16 v[44:47], v[184:187], v[228:231], v[44:47]
	v_mfma_f32_16x16x32_bf16 v[36:39], v[200:203], v[228:231], v[36:39]
	v_mfma_f32_16x16x32_bf16 v[28:31], v[184:187], v[236:239], v[28:31]
	v_mfma_f32_16x16x32_bf16 v[20:23], v[200:203], v[236:239], v[20:23]
	s_barrier
	s_setprio 0
	s_add_i32 s35, s35, 2
	s_add_u32 s2, s2, 0x1000
	s_addc_u32 s3, s3, 0
	s_add_u32 s33, s33, 0x100
	s_addc_u32 s34, s34, 0
	s_cmp_gt_u32 s35, 29
	s_cbranch_scc0 .LBB0_256

.LBB0_488:
	s_ashr_i32 s17, s16, 31
	s_lshl_b64 s[8:9], s[16:17], 20
	v_readlane_b32 s18, v254, 39
	v_readlane_b32 s19, v254, 40
	s_add_u32 s18, s18, s8
	s_addc_u32 s19, s19, s9
	s_and_b64 s[8:9], s[36:37], exec
	s_cselect_b32 s3, s19, s23
	s_cselect_b32 s6, s18, s22
	s_ashr_i32 s15, s14, 31
	s_lshl_b64 s[8:9], s[14:15], 20
	s_add_u32 s20, s28, s8
	s_addc_u32 s21, s29, s9
	s_and_b64 s[8:9], s[36:37], exec
	s_cselect_b32 s8, s21, s27
	s_cselect_b32 s9, s20, s26
	s_add_u32 s22, s22, 0x80800
	s_addc_u32 s23, s23, 0
	s_add_u32 s15, s26, 0x100
	s_addc_u32 s17, s27, 0
	s_mov_b32 s33, -2
	s_add_u32 s26, s22, 0xfff80800
	s_addc_u32 s27, s23, -1
	s_add_i32 s34, 0, 0x10000
	s_cmp_eq_u32 s33, 28
	s_cselect_b32 s39, s3, s27
	s_cselect_b32 s38, s6, s26
	s_cselect_b32 s27, s8, s17
	s_cselect_b32 s26, s9, s15
	s_add_i32 s53, 0, 0x14000
	v_add_u32_e32 v144, s34, v168
	v_add_u32_e32 v160, s53, v168
	ds_read_b128 v[4:7], v144
	ds_read_b128 v[8:11], v144 offset:1024
	ds_read_b128 v[140:143], v144 offset:2048
	ds_read_b128 v[144:147], v144 offset:3072
	ds_read_b128 v[172:175], v160
	ds_read_b128 v[176:179], v160 offset:1024
	ds_read_b128 v[180:183], v160 offset:2048
	ds_read_b128 v[184:187], v160 offset:3072
	s_add_i32 m0, s13, 0xc000
	ds_read_b128 v[188:191], v170
	ds_read_b128 v[192:195], v170 offset:1024
	ds_read_b128 v[196:199], v170 offset:2048
	ds_read_b128 v[200:203], v170 offset:3072
	ds_read_b128 v[204:207], v170 offset:4096
	ds_read_b128 v[212:215], v170 offset:5120
	ds_read_b128 v[216:219], v170 offset:6144
	ds_read_b128 v[220:223], v170 offset:7168
	global_load_lds_dwordx4 v156, s[22:23]
	s_add_i32 m0, s13, 0xe000
	s_nop 0
	global_load_lds_dwordx4 v158, s[22:23]
	s_waitcnt vmcnt(8)
	s_waitcnt lgkmcnt(0)
	s_setprio 1
	s_barrier
	v_mfma_f32_16x16x32_bf16 v[136:139], v[4:7], v[188:191], 0
	v_mfma_f32_16x16x32_bf16 v[132:135], v[140:143], v[188:191], 0
	v_mfma_f32_16x16x32_bf16 v[128:131], v[4:7], v[196:199], 0
	v_mfma_f32_16x16x32_bf16 v[120:123], v[140:143], v[196:199], 0
	v_mfma_f32_16x16x32_bf16 v[112:115], v[4:7], v[204:207], 0
	v_mfma_f32_16x16x32_bf16 v[104:107], v[140:143], v[204:207], 0
	v_mfma_f32_16x16x32_bf16 v[96:99], v[4:7], v[216:219], 0
	v_mfma_f32_16x16x32_bf16 v[88:91], v[140:143], v[216:219], 0
	v_mfma_f32_16x16x32_bf16 v[136:139], v[8:11], v[192:195], v[136:139]
	v_mfma_f32_16x16x32_bf16 v[132:135], v[144:147], v[192:195], v[132:135]
	v_mfma_f32_16x16x32_bf16 v[128:131], v[8:11], v[200:203], v[128:131]
	v_mfma_f32_16x16x32_bf16 v[120:123], v[144:147], v[200:203], v[120:123]
	v_mfma_f32_16x16x32_bf16 v[112:115], v[8:11], v[212:215], v[112:115]
	v_mfma_f32_16x16x32_bf16 v[104:107], v[144:147], v[212:215], v[104:107]
	v_mfma_f32_16x16x32_bf16 v[96:99], v[8:11], v[220:223], v[96:99]
	v_mfma_f32_16x16x32_bf16 v[88:91], v[144:147], v[220:223], v[88:91]
	v_mfma_f32_16x16x32_bf16 v[124:127], v[172:175], v[188:191], 0
	v_mfma_f32_16x16x32_bf16 v[116:119], v[180:183], v[188:191], 0
	v_mfma_f32_16x16x32_bf16 v[108:111], v[172:175], v[196:199], 0
	v_mfma_f32_16x16x32_bf16 v[100:103], v[180:183], v[196:199], 0
	v_mfma_f32_16x16x32_bf16 v[92:95], v[172:175], v[204:207], 0
	v_mfma_f32_16x16x32_bf16 v[84:87], v[180:183], v[204:207], 0
	v_mfma_f32_16x16x32_bf16 v[80:83], v[172:175], v[216:219], 0
	v_mfma_f32_16x16x32_bf16 v[76:79], v[180:183], v[216:219], 0
	v_mfma_f32_16x16x32_bf16 v[124:127], v[176:179], v[192:195], v[124:127]
	v_mfma_f32_16x16x32_bf16 v[116:119], v[184:187], v[192:195], v[116:119]
	v_mfma_f32_16x16x32_bf16 v[108:111], v[176:179], v[200:203], v[108:111]
	v_mfma_f32_16x16x32_bf16 v[100:103], v[184:187], v[200:203], v[100:103]
	v_mfma_f32_16x16x32_bf16 v[92:95], v[176:179], v[212:215], v[92:95]
	v_mfma_f32_16x16x32_bf16 v[84:87], v[184:187], v[212:215], v[84:87]
	v_mfma_f32_16x16x32_bf16 v[80:83], v[176:179], v[220:223], v[80:83]
	v_mfma_f32_16x16x32_bf16 v[76:79], v[184:187], v[220:223], v[76:79]
	s_barrier
	s_setprio 0
	s_add_i32 s34, s34, s7
	s_add_u32 s98, s26, 0x80
	s_addc_u32 s99, s27, 0
	s_add_u32 s100, s38, 0x800
	s_addc_u32 s101, s39, 0
	s_mov_b32 m0, s34
	ds_read_b128 v[188:191], v170 offset:16384
	ds_read_b128 v[192:195], v170 offset:17408
	ds_read_b128 v[196:199], v170 offset:18432
	ds_read_b128 v[200:203], v170 offset:19456
	ds_read_b128 v[204:207], v170 offset:20480
	ds_read_b128 v[212:215], v170 offset:21504
	ds_read_b128 v[216:219], v170 offset:22528
	ds_read_b128 v[220:223], v170 offset:23552
	global_load_lds_dwordx4 v2, s[26:27]
	s_add_i32 m0, s34, 0x2000
	s_add_u32 s34, s26, 0x80000
	s_addc_u32 s35, s27, 0
	s_add_i32 s53, s53, s7
	global_load_lds_dwordx4 v148, s[26:27]
	s_mov_b32 m0, s53
	s_nop 0
	global_load_lds_dwordx4 v2, s[34:35]
	s_add_i32 m0, s53, 0x2000
	s_nop 0
	global_load_lds_dwordx4 v148, s[34:35]
	s_mov_b32 m0, s13
	s_nop 0
	global_load_lds_dwordx4 v152, s[38:39]
	s_mov_b32 m0, s46
	s_nop 0
	global_load_lds_dwordx4 v150, s[38:39]
	s_waitcnt vmcnt(8)
	s_waitcnt lgkmcnt(0)
	s_setprio 1
	s_barrier
	v_mfma_f32_16x16x32_bf16 v[72:75], v[4:7], v[188:191], 0
	v_mfma_f32_16x16x32_bf16 v[68:71], v[140:143], v[188:191], 0
	v_mfma_f32_16x16x32_bf16 v[64:67], v[4:7], v[196:199], 0
	v_mfma_f32_16x16x32_bf16 v[56:59], v[140:143], v[196:199], 0
	v_mfma_f32_16x16x32_bf16 v[48:51], v[4:7], v[204:207], 0
	v_mfma_f32_16x16x32_bf16 v[40:43], v[140:143], v[204:207], 0
	v_mfma_f32_16x16x32_bf16 v[4:7], v[4:7], v[216:219], 0
	v_mfma_f32_16x16x32_bf16 v[72:75], v[8:11], v[192:195], v[72:75]
	v_mfma_f32_16x16x32_bf16 v[68:71], v[144:147], v[192:195], v[68:71]
	v_mfma_f32_16x16x32_bf16 v[64:67], v[8:11], v[200:203], v[64:67]
	v_mfma_f32_16x16x32_bf16 v[56:59], v[144:147], v[200:203], v[56:59]
	v_mfma_f32_16x16x32_bf16 v[48:51], v[8:11], v[212:215], v[48:51]
	v_mfma_f32_16x16x32_bf16 v[40:43], v[144:147], v[212:215], v[40:43]
	v_mfma_f32_16x16x32_bf16 v[4:7], v[8:11], v[220:223], v[4:7]
	v_mfma_f32_16x16x32_bf16 v[8:11], v[140:143], v[216:219], 0
	v_mfma_f32_16x16x32_bf16 v[8:11], v[144:147], v[220:223], v[8:11]
	v_mfma_f32_16x16x32_bf16 v[24:27], v[172:175], v[188:191], 0
	v_mfma_f32_16x16x32_bf16 v[60:63], v[176:179], v[192:195], v[24:27]
	v_mfma_f32_16x16x32_bf16 v[24:27], v[180:183], v[188:191], 0
	v_mfma_f32_16x16x32_bf16 v[52:55], v[184:187], v[192:195], v[24:27]
	v_mfma_f32_16x16x32_bf16 v[24:27], v[172:175], v[196:199], 0
	v_mfma_f32_16x16x32_bf16 v[44:47], v[176:179], v[200:203], v[24:27]
	v_mfma_f32_16x16x32_bf16 v[24:27], v[180:183], v[196:199], 0
	v_mfma_f32_16x16x32_bf16 v[36:39], v[184:187], v[200:203], v[24:27]
	v_mfma_f32_16x16x32_bf16 v[24:27], v[172:175], v[204:207], 0
	v_mfma_f32_16x16x32_bf16 v[20:23], v[180:183], v[204:207], 0
	v_mfma_f32_16x16x32_bf16 v[16:19], v[172:175], v[216:219], 0
	v_mfma_f32_16x16x32_bf16 v[12:15], v[180:183], v[216:219], 0
	v_mfma_f32_16x16x32_bf16 v[28:31], v[176:179], v[212:215], v[24:27]
	v_mfma_f32_16x16x32_bf16 v[20:23], v[184:187], v[212:215], v[20:23]
	v_mfma_f32_16x16x32_bf16 v[16:19], v[176:179], v[220:223], v[16:19]
	v_mfma_f32_16x16x32_bf16 v[12:15], v[184:187], v[220:223], v[12:15]
	s_barrier
	s_setprio 0
	s_add_i32 s53, 0, 0x18000
	s_add_i32 s54, 0, 0x1c000
	v_add_u32_e32 v144, s53, v168
	v_add_u32_e32 v171, s54, v168
	ds_read_b128 v[24:27], v144
	ds_read_b128 v[32:35], v144 offset:1024
	ds_read_b128 v[140:143], v144 offset:2048
	ds_read_b128 v[144:147], v144 offset:3072
	ds_read_b128 v[172:175], v171
	ds_read_b128 v[176:179], v171 offset:1024
	ds_read_b128 v[180:183], v171 offset:2048
	ds_read_b128 v[184:187], v171 offset:3072
	s_add_u32 s34, s38, 0x80000
	s_addc_u32 s35, s39, 0
	s_mov_b32 m0, s47
	ds_read_b128 v[188:191], v170 offset:32768
	ds_read_b128 v[192:195], v170 offset:33792
	ds_read_b128 v[196:199], v170 offset:34816
	ds_read_b128 v[200:203], v170 offset:35840
	ds_read_b128 v[204:207], v170 offset:36864
	ds_read_b128 v[212:215], v170 offset:37888
	ds_read_b128 v[216:219], v170 offset:38912
	ds_read_b128 v[220:223], v170 offset:39936
	global_load_lds_dwordx4 v152, s[34:35]
	s_mov_b32 m0, s48
	s_nop 0
	global_load_lds_dwordx4 v150, s[34:35]
	s_waitcnt vmcnt(8)
	s_waitcnt lgkmcnt(0)
	s_setprio 1
	s_barrier
	v_mfma_f32_16x16x32_bf16 v[136:139], v[24:27], v[188:191], v[136:139]
	v_mfma_f32_16x16x32_bf16 v[132:135], v[140:143], v[188:191], v[132:135]
	v_mfma_f32_16x16x32_bf16 v[128:131], v[24:27], v[196:199], v[128:131]
	v_mfma_f32_16x16x32_bf16 v[120:123], v[140:143], v[196:199], v[120:123]
	v_mfma_f32_16x16x32_bf16 v[112:115], v[24:27], v[204:207], v[112:115]
	v_mfma_f32_16x16x32_bf16 v[104:107], v[140:143], v[204:207], v[104:107]
	v_mfma_f32_16x16x32_bf16 v[96:99], v[24:27], v[216:219], v[96:99]
	v_mfma_f32_16x16x32_bf16 v[88:91], v[140:143], v[216:219], v[88:91]
	v_mfma_f32_16x16x32_bf16 v[136:139], v[32:35], v[192:195], v[136:139]
	v_mfma_f32_16x16x32_bf16 v[132:135], v[144:147], v[192:195], v[132:135]
	v_mfma_f32_16x16x32_bf16 v[128:131], v[32:35], v[200:203], v[128:131]
	v_mfma_f32_16x16x32_bf16 v[120:123], v[144:147], v[200:203], v[120:123]
	v_mfma_f32_16x16x32_bf16 v[112:115], v[32:35], v[212:215], v[112:115]
	v_mfma_f32_16x16x32_bf16 v[104:107], v[144:147], v[212:215], v[104:107]
	v_mfma_f32_16x16x32_bf16 v[96:99], v[32:35], v[220:223], v[96:99]
	v_mfma_f32_16x16x32_bf16 v[88:91], v[144:147], v[220:223], v[88:91]
	v_mfma_f32_16x16x32_bf16 v[124:127], v[172:175], v[188:191], v[124:127]
	v_mfma_f32_16x16x32_bf16 v[116:119], v[180:183], v[188:191], v[116:119]
	v_mfma_f32_16x16x32_bf16 v[108:111], v[172:175], v[196:199], v[108:111]
	v_mfma_f32_16x16x32_bf16 v[100:103], v[180:183], v[196:199], v[100:103]
	v_mfma_f32_16x16x32_bf16 v[92:95], v[172:175], v[204:207], v[92:95]
	v_mfma_f32_16x16x32_bf16 v[84:87], v[180:183], v[204:207], v[84:87]
	v_mfma_f32_16x16x32_bf16 v[80:83], v[172:175], v[216:219], v[80:83]
	v_mfma_f32_16x16x32_bf16 v[76:79], v[180:183], v[216:219], v[76:79]
	v_mfma_f32_16x16x32_bf16 v[124:127], v[176:179], v[192:195], v[124:127]
	v_mfma_f32_16x16x32_bf16 v[116:119], v[184:187], v[192:195], v[116:119]
	v_mfma_f32_16x16x32_bf16 v[108:111], v[176:179], v[200:203], v[108:111]
	v_mfma_f32_16x16x32_bf16 v[100:103], v[184:187], v[200:203], v[100:103]
	v_mfma_f32_16x16x32_bf16 v[92:95], v[176:179], v[212:215], v[92:95]
	v_mfma_f32_16x16x32_bf16 v[84:87], v[184:187], v[212:215], v[84:87]
	v_mfma_f32_16x16x32_bf16 v[80:83], v[176:179], v[220:223], v[80:83]
	v_mfma_f32_16x16x32_bf16 v[76:79], v[184:187], v[220:223], v[76:79]
	s_barrier
	s_setprio 0
	s_add_i32 s34, s53, s7
	s_mov_b32 m0, s34
	ds_read_b128 v[188:191], v170 offset:49152
	ds_read_b128 v[192:195], v170 offset:50176
	ds_read_b128 v[196:199], v170 offset:51200
	ds_read_b128 v[200:203], v170 offset:52224
	ds_read_b128 v[204:207], v170 offset:53248
	ds_read_b128 v[212:215], v170 offset:54272
	ds_read_b128 v[216:219], v170 offset:55296
	ds_read_b128 v[220:223], v170 offset:56320
	global_load_lds_dwordx4 v2, s[98:99]
	s_add_i32 m0, s34, 0x2000
	s_add_u32 s26, s26, 0x80080
	s_addc_u32 s27, s27, 0
	s_add_i32 s34, s54, s7
	global_load_lds_dwordx4 v148, s[98:99]
	s_mov_b32 m0, s34
	s_nop 0
	global_load_lds_dwordx4 v2, s[26:27]
	s_add_i32 m0, s34, 0x2000
	s_nop 0
	global_load_lds_dwordx4 v148, s[26:27]
	s_mov_b32 m0, s49
	s_nop 0
	global_load_lds_dwordx4 v152, s[100:101]
	s_mov_b32 m0, s50
	s_nop 0
	global_load_lds_dwordx4 v150, s[100:101]
	s_waitcnt vmcnt(8)
	s_waitcnt lgkmcnt(0)
	s_setprio 1
	s_barrier
	v_mfma_f32_16x16x32_bf16 v[72:75], v[24:27], v[188:191], v[72:75]
	v_mfma_f32_16x16x32_bf16 v[64:67], v[24:27], v[196:199], v[64:67]
	v_mfma_f32_16x16x32_bf16 v[48:51], v[24:27], v[204:207], v[48:51]
	v_mfma_f32_16x16x32_bf16 v[4:7], v[24:27], v[216:219], v[4:7]
	v_mfma_f32_16x16x32_bf16 v[72:75], v[32:35], v[192:195], v[72:75]
	v_mfma_f32_16x16x32_bf16 v[68:71], v[140:143], v[188:191], v[68:71]
	v_mfma_f32_16x16x32_bf16 v[64:67], v[32:35], v[200:203], v[64:67]
	v_mfma_f32_16x16x32_bf16 v[56:59], v[140:143], v[196:199], v[56:59]
	v_mfma_f32_16x16x32_bf16 v[48:51], v[32:35], v[212:215], v[48:51]
	v_mfma_f32_16x16x32_bf16 v[40:43], v[140:143], v[204:207], v[40:43]
	v_mfma_f32_16x16x32_bf16 v[32:35], v[32:35], v[220:223], v[4:7]
	v_mfma_f32_16x16x32_bf16 v[4:7], v[140:143], v[216:219], v[8:11]
	v_mfma_f32_16x16x32_bf16 v[68:71], v[144:147], v[192:195], v[68:71]
	v_mfma_f32_16x16x32_bf16 v[56:59], v[144:147], v[200:203], v[56:59]
	v_mfma_f32_16x16x32_bf16 v[40:43], v[144:147], v[212:215], v[40:43]
	v_mfma_f32_16x16x32_bf16 v[24:27], v[144:147], v[220:223], v[4:7]
	v_mfma_f32_16x16x32_bf16 v[4:7], v[172:175], v[188:191], v[60:63]
	v_mfma_f32_16x16x32_bf16 v[60:63], v[176:179], v[192:195], v[4:7]
	v_mfma_f32_16x16x32_bf16 v[4:7], v[180:183], v[188:191], v[52:55]
	v_mfma_f32_16x16x32_bf16 v[52:55], v[184:187], v[192:195], v[4:7]
	v_mfma_f32_16x16x32_bf16 v[4:7], v[172:175], v[196:199], v[44:47]
	v_mfma_f32_16x16x32_bf16 v[44:47], v[176:179], v[200:203], v[4:7]
	v_mfma_f32_16x16x32_bf16 v[4:7], v[180:183], v[196:199], v[36:39]
	v_mfma_f32_16x16x32_bf16 v[36:39], v[184:187], v[200:203], v[4:7]
	v_mfma_f32_16x16x32_bf16 v[4:7], v[172:175], v[204:207], v[28:31]
	v_mfma_f32_16x16x32_bf16 v[28:31], v[176:179], v[212:215], v[4:7]
	v_mfma_f32_16x16x32_bf16 v[4:7], v[180:183], v[204:207], v[20:23]
	v_mfma_f32_16x16x32_bf16 v[20:23], v[184:187], v[212:215], v[4:7]
	v_mfma_f32_16x16x32_bf16 v[4:7], v[172:175], v[216:219], v[16:19]
	v_mfma_f32_16x16x32_bf16 v[16:19], v[176:179], v[220:223], v[4:7]
	v_mfma_f32_16x16x32_bf16 v[4:7], v[180:183], v[216:219], v[12:15]
	v_mfma_f32_16x16x32_bf16 v[12:15], v[184:187], v[220:223], v[4:7]
	s_barrier
	s_setprio 0
	s_add_i32 s33, s33, 2
	s_add_u32 s22, s22, 0x1000
	s_addc_u32 s23, s23, 0
	s_add_u32 s15, s15, 0x100
	s_addc_u32 s17, s17, 0
	s_cmp_gt_u32 s33, 29
	s_cbranch_scc0 .LBB0_489
	s_branch .Lpeel_done_489
.LBB0_489:
	s_add_u32 s26, s22, 0xfff80800
	s_addc_u32 s27, s23, -1
	s_add_i32 s34, 0, 0x10000
	s_cmp_eq_u32 s33, 28
	s_cselect_b32 s39, s3, s27
	s_cselect_b32 s38, s6, s26
	s_cselect_b32 s27, s8, s17
	s_cselect_b32 s26, s9, s15
	s_add_i32 s53, 0, 0x14000
	v_add_u32_e32 v144, s34, v168
	v_add_u32_e32 v160, s53, v168
	ds_read_b128 v[4:7], v144
	ds_read_b128 v[8:11], v144 offset:1024
	ds_read_b128 v[140:143], v144 offset:2048
	ds_read_b128 v[144:147], v144 offset:3072
	ds_read_b128 v[172:175], v160
	ds_read_b128 v[176:179], v160 offset:1024
	ds_read_b128 v[180:183], v160 offset:2048
	ds_read_b128 v[184:187], v160 offset:3072
	s_add_i32 m0, s13, 0xc000
	ds_read_b128 v[188:191], v170
	ds_read_b128 v[192:195], v170 offset:1024
	ds_read_b128 v[196:199], v170 offset:2048
	ds_read_b128 v[200:203], v170 offset:3072
	ds_read_b128 v[204:207], v170 offset:4096
	ds_read_b128 v[212:215], v170 offset:5120
	ds_read_b128 v[216:219], v170 offset:6144
	ds_read_b128 v[220:223], v170 offset:7168
	global_load_lds_dwordx4 v156, s[22:23]
	s_add_i32 m0, s13, 0xe000
	s_nop 0
	global_load_lds_dwordx4 v158, s[22:23]
	s_waitcnt vmcnt(8)
	s_waitcnt lgkmcnt(0)
	s_setprio 1
	s_barrier
	v_mfma_f32_16x16x32_bf16 v[136:139], v[4:7], v[188:191], v[136:139]
	v_mfma_f32_16x16x32_bf16 v[132:135], v[140:143], v[188:191], v[132:135]
	v_mfma_f32_16x16x32_bf16 v[128:131], v[4:7], v[196:199], v[128:131]
	v_mfma_f32_16x16x32_bf16 v[120:123], v[140:143], v[196:199], v[120:123]
	v_mfma_f32_16x16x32_bf16 v[112:115], v[4:7], v[204:207], v[112:115]
	v_mfma_f32_16x16x32_bf16 v[104:107], v[140:143], v[204:207], v[104:107]
	v_mfma_f32_16x16x32_bf16 v[96:99], v[4:7], v[216:219], v[96:99]
	v_mfma_f32_16x16x32_bf16 v[88:91], v[140:143], v[216:219], v[88:91]
	v_mfma_f32_16x16x32_bf16 v[136:139], v[8:11], v[192:195], v[136:139]
	v_mfma_f32_16x16x32_bf16 v[132:135], v[144:147], v[192:195], v[132:135]
	v_mfma_f32_16x16x32_bf16 v[128:131], v[8:11], v[200:203], v[128:131]
	v_mfma_f32_16x16x32_bf16 v[120:123], v[144:147], v[200:203], v[120:123]
	v_mfma_f32_16x16x32_bf16 v[112:115], v[8:11], v[212:215], v[112:115]
	v_mfma_f32_16x16x32_bf16 v[104:107], v[144:147], v[212:215], v[104:107]
	v_mfma_f32_16x16x32_bf16 v[96:99], v[8:11], v[220:223], v[96:99]
	v_mfma_f32_16x16x32_bf16 v[88:91], v[144:147], v[220:223], v[88:91]
	v_mfma_f32_16x16x32_bf16 v[124:127], v[172:175], v[188:191], v[124:127]
	v_mfma_f32_16x16x32_bf16 v[116:119], v[180:183], v[188:191], v[116:119]
	v_mfma_f32_16x16x32_bf16 v[108:111], v[172:175], v[196:199], v[108:111]
	v_mfma_f32_16x16x32_bf16 v[100:103], v[180:183], v[196:199], v[100:103]
	v_mfma_f32_16x16x32_bf16 v[92:95], v[172:175], v[204:207], v[92:95]
	v_mfma_f32_16x16x32_bf16 v[84:87], v[180:183], v[204:207], v[84:87]
	v_mfma_f32_16x16x32_bf16 v[80:83], v[172:175], v[216:219], v[80:83]
	v_mfma_f32_16x16x32_bf16 v[76:79], v[180:183], v[216:219], v[76:79]
	v_mfma_f32_16x16x32_bf16 v[124:127], v[176:179], v[192:195], v[124:127]
	v_mfma_f32_16x16x32_bf16 v[116:119], v[184:187], v[192:195], v[116:119]
	v_mfma_f32_16x16x32_bf16 v[108:111], v[176:179], v[200:203], v[108:111]
	v_mfma_f32_16x16x32_bf16 v[100:103], v[184:187], v[200:203], v[100:103]
	v_mfma_f32_16x16x32_bf16 v[92:95], v[176:179], v[212:215], v[92:95]
	v_mfma_f32_16x16x32_bf16 v[84:87], v[184:187], v[212:215], v[84:87]
	v_mfma_f32_16x16x32_bf16 v[80:83], v[176:179], v[220:223], v[80:83]
	v_mfma_f32_16x16x32_bf16 v[76:79], v[184:187], v[220:223], v[76:79]
	s_barrier
	s_setprio 0
	s_add_i32 s34, s34, s7
	s_add_u32 s98, s26, 0x80
	s_addc_u32 s99, s27, 0
	s_add_u32 s100, s38, 0x800
	s_addc_u32 s101, s39, 0
	s_mov_b32 m0, s34
	ds_read_b128 v[188:191], v170 offset:16384
	ds_read_b128 v[192:195], v170 offset:17408
	ds_read_b128 v[196:199], v170 offset:18432
	ds_read_b128 v[200:203], v170 offset:19456
	ds_read_b128 v[204:207], v170 offset:20480
	ds_read_b128 v[212:215], v170 offset:21504
	ds_read_b128 v[216:219], v170 offset:22528
	ds_read_b128 v[220:223], v170 offset:23552
	global_load_lds_dwordx4 v2, s[26:27]
	s_add_i32 m0, s34, 0x2000
	s_add_u32 s34, s26, 0x80000
	s_addc_u32 s35, s27, 0
	s_add_i32 s53, s53, s7
	global_load_lds_dwordx4 v148, s[26:27]
	s_mov_b32 m0, s53
	s_nop 0
	global_load_lds_dwordx4 v2, s[34:35]
	s_add_i32 m0, s53, 0x2000
	s_nop 0
	global_load_lds_dwordx4 v148, s[34:35]
	s_mov_b32 m0, s13
	s_nop 0
	global_load_lds_dwordx4 v152, s[38:39]
	s_mov_b32 m0, s46
	s_nop 0
	global_load_lds_dwordx4 v150, s[38:39]
	s_waitcnt vmcnt(8)
	s_waitcnt lgkmcnt(0)
	s_setprio 1
	s_barrier
	v_mfma_f32_16x16x32_bf16 v[72:75], v[4:7], v[188:191], v[72:75]
	v_mfma_f32_16x16x32_bf16 v[68:71], v[140:143], v[188:191], v[68:71]
	v_mfma_f32_16x16x32_bf16 v[64:67], v[4:7], v[196:199], v[64:67]
	v_mfma_f32_16x16x32_bf16 v[56:59], v[140:143], v[196:199], v[56:59]
	v_mfma_f32_16x16x32_bf16 v[48:51], v[4:7], v[204:207], v[48:51]
	v_mfma_f32_16x16x32_bf16 v[40:43], v[140:143], v[204:207], v[40:43]
	v_mfma_f32_16x16x32_bf16 v[4:7], v[4:7], v[216:219], v[32:35]
	v_mfma_f32_16x16x32_bf16 v[72:75], v[8:11], v[192:195], v[72:75]
	v_mfma_f32_16x16x32_bf16 v[68:71], v[144:147], v[192:195], v[68:71]
	v_mfma_f32_16x16x32_bf16 v[64:67], v[8:11], v[200:203], v[64:67]
	v_mfma_f32_16x16x32_bf16 v[56:59], v[144:147], v[200:203], v[56:59]
	v_mfma_f32_16x16x32_bf16 v[48:51], v[8:11], v[212:215], v[48:51]
	v_mfma_f32_16x16x32_bf16 v[40:43], v[144:147], v[212:215], v[40:43]
	v_mfma_f32_16x16x32_bf16 v[4:7], v[8:11], v[220:223], v[4:7]
	v_mfma_f32_16x16x32_bf16 v[8:11], v[140:143], v[216:219], v[24:27]
	v_mfma_f32_16x16x32_bf16 v[8:11], v[144:147], v[220:223], v[8:11]
	v_mfma_f32_16x16x32_bf16 v[24:27], v[172:175], v[188:191], v[60:63]
	v_mfma_f32_16x16x32_bf16 v[60:63], v[176:179], v[192:195], v[24:27]
	v_mfma_f32_16x16x32_bf16 v[24:27], v[180:183], v[188:191], v[52:55]
	v_mfma_f32_16x16x32_bf16 v[52:55], v[184:187], v[192:195], v[24:27]
	v_mfma_f32_16x16x32_bf16 v[24:27], v[172:175], v[196:199], v[44:47]
	v_mfma_f32_16x16x32_bf16 v[44:47], v[176:179], v[200:203], v[24:27]
	v_mfma_f32_16x16x32_bf16 v[24:27], v[180:183], v[196:199], v[36:39]
	v_mfma_f32_16x16x32_bf16 v[36:39], v[184:187], v[200:203], v[24:27]
	v_mfma_f32_16x16x32_bf16 v[24:27], v[172:175], v[204:207], v[28:31]
	v_mfma_f32_16x16x32_bf16 v[20:23], v[180:183], v[204:207], v[20:23]
	v_mfma_f32_16x16x32_bf16 v[16:19], v[172:175], v[216:219], v[16:19]
	v_mfma_f32_16x16x32_bf16 v[12:15], v[180:183], v[216:219], v[12:15]
	v_mfma_f32_16x16x32_bf16 v[28:31], v[176:179], v[212:215], v[24:27]
	v_mfma_f32_16x16x32_bf16 v[20:23], v[184:187], v[212:215], v[20:23]
	v_mfma_f32_16x16x32_bf16 v[16:19], v[176:179], v[220:223], v[16:19]
	v_mfma_f32_16x16x32_bf16 v[12:15], v[184:187], v[220:223], v[12:15]
	s_barrier
	s_setprio 0
	s_add_i32 s53, 0, 0x18000
	s_add_i32 s54, 0, 0x1c000
	v_add_u32_e32 v144, s53, v168
	v_add_u32_e32 v171, s54, v168
	ds_read_b128 v[24:27], v144
	ds_read_b128 v[32:35], v144 offset:1024
	ds_read_b128 v[140:143], v144 offset:2048
	ds_read_b128 v[144:147], v144 offset:3072
	ds_read_b128 v[172:175], v171
	ds_read_b128 v[176:179], v171 offset:1024
	ds_read_b128 v[180:183], v171 offset:2048
	ds_read_b128 v[184:187], v171 offset:3072
	s_add_u32 s34, s38, 0x80000
	s_addc_u32 s35, s39, 0
	s_mov_b32 m0, s47
	ds_read_b128 v[188:191], v170 offset:32768
	ds_read_b128 v[192:195], v170 offset:33792
	ds_read_b128 v[196:199], v170 offset:34816
	ds_read_b128 v[200:203], v170 offset:35840
	ds_read_b128 v[204:207], v170 offset:36864
	ds_read_b128 v[212:215], v170 offset:37888
	ds_read_b128 v[216:219], v170 offset:38912
	ds_read_b128 v[220:223], v170 offset:39936
	global_load_lds_dwordx4 v152, s[34:35]
	s_mov_b32 m0, s48
	s_nop 0
	global_load_lds_dwordx4 v150, s[34:35]
	s_waitcnt vmcnt(8)
	s_waitcnt lgkmcnt(0)
	s_setprio 1
	s_barrier
	v_mfma_f32_16x16x32_bf16 v[136:139], v[24:27], v[188:191], v[136:139]
	v_mfma_f32_16x16x32_bf16 v[132:135], v[140:143], v[188:191], v[132:135]
	v_mfma_f32_16x16x32_bf16 v[128:131], v[24:27], v[196:199], v[128:131]
	v_mfma_f32_16x16x32_bf16 v[120:123], v[140:143], v[196:199], v[120:123]
	v_mfma_f32_16x16x32_bf16 v[112:115], v[24:27], v[204:207], v[112:115]
	v_mfma_f32_16x16x32_bf16 v[104:107], v[140:143], v[204:207], v[104:107]
	v_mfma_f32_16x16x32_bf16 v[96:99], v[24:27], v[216:219], v[96:99]
	v_mfma_f32_16x16x32_bf16 v[88:91], v[140:143], v[216:219], v[88:91]
	v_mfma_f32_16x16x32_bf16 v[136:139], v[32:35], v[192:195], v[136:139]
	v_mfma_f32_16x16x32_bf16 v[132:135], v[144:147], v[192:195], v[132:135]
	v_mfma_f32_16x16x32_bf16 v[128:131], v[32:35], v[200:203], v[128:131]
	v_mfma_f32_16x16x32_bf16 v[120:123], v[144:147], v[200:203], v[120:123]
	v_mfma_f32_16x16x32_bf16 v[112:115], v[32:35], v[212:215], v[112:115]
	v_mfma_f32_16x16x32_bf16 v[104:107], v[144:147], v[212:215], v[104:107]
	v_mfma_f32_16x16x32_bf16 v[96:99], v[32:35], v[220:223], v[96:99]
	v_mfma_f32_16x16x32_bf16 v[88:91], v[144:147], v[220:223], v[88:91]
	v_mfma_f32_16x16x32_bf16 v[124:127], v[172:175], v[188:191], v[124:127]
	v_mfma_f32_16x16x32_bf16 v[116:119], v[180:183], v[188:191], v[116:119]
	v_mfma_f32_16x16x32_bf16 v[108:111], v[172:175], v[196:199], v[108:111]
	v_mfma_f32_16x16x32_bf16 v[100:103], v[180:183], v[196:199], v[100:103]
	v_mfma_f32_16x16x32_bf16 v[92:95], v[172:175], v[204:207], v[92:95]
	v_mfma_f32_16x16x32_bf16 v[84:87], v[180:183], v[204:207], v[84:87]
	v_mfma_f32_16x16x32_bf16 v[80:83], v[172:175], v[216:219], v[80:83]
	v_mfma_f32_16x16x32_bf16 v[76:79], v[180:183], v[216:219], v[76:79]
	v_mfma_f32_16x16x32_bf16 v[124:127], v[176:179], v[192:195], v[124:127]
	v_mfma_f32_16x16x32_bf16 v[116:119], v[184:187], v[192:195], v[116:119]
	v_mfma_f32_16x16x32_bf16 v[108:111], v[176:179], v[200:203], v[108:111]
	v_mfma_f32_16x16x32_bf16 v[100:103], v[184:187], v[200:203], v[100:103]
	v_mfma_f32_16x16x32_bf16 v[92:95], v[176:179], v[212:215], v[92:95]
	v_mfma_f32_16x16x32_bf16 v[84:87], v[184:187], v[212:215], v[84:87]
	v_mfma_f32_16x16x32_bf16 v[80:83], v[176:179], v[220:223], v[80:83]
	v_mfma_f32_16x16x32_bf16 v[76:79], v[184:187], v[220:223], v[76:79]
	s_barrier
	s_setprio 0
	s_add_i32 s34, s53, s7
	s_mov_b32 m0, s34
	ds_read_b128 v[188:191], v170 offset:49152
	ds_read_b128 v[192:195], v170 offset:50176
	ds_read_b128 v[196:199], v170 offset:51200
	ds_read_b128 v[200:203], v170 offset:52224
	ds_read_b128 v[204:207], v170 offset:53248
	ds_read_b128 v[212:215], v170 offset:54272
	ds_read_b128 v[216:219], v170 offset:55296
	ds_read_b128 v[220:223], v170 offset:56320
	global_load_lds_dwordx4 v2, s[98:99]
	s_add_i32 m0, s34, 0x2000
	s_add_u32 s26, s26, 0x80080
	s_addc_u32 s27, s27, 0
	s_add_i32 s34, s54, s7
	global_load_lds_dwordx4 v148, s[98:99]
	s_mov_b32 m0, s34
	s_nop 0
	global_load_lds_dwordx4 v2, s[26:27]
	s_add_i32 m0, s34, 0x2000
	s_nop 0
	global_load_lds_dwordx4 v148, s[26:27]
	s_mov_b32 m0, s49
	s_nop 0
	global_load_lds_dwordx4 v152, s[100:101]
	s_mov_b32 m0, s50
	s_nop 0
	global_load_lds_dwordx4 v150, s[100:101]
	s_waitcnt vmcnt(8)
	s_waitcnt lgkmcnt(0)
	s_setprio 1
	s_barrier
	v_mfma_f32_16x16x32_bf16 v[72:75], v[24:27], v[188:191], v[72:75]
	v_mfma_f32_16x16x32_bf16 v[64:67], v[24:27], v[196:199], v[64:67]
	v_mfma_f32_16x16x32_bf16 v[48:51], v[24:27], v[204:207], v[48:51]
	v_mfma_f32_16x16x32_bf16 v[4:7], v[24:27], v[216:219], v[4:7]
	v_mfma_f32_16x16x32_bf16 v[72:75], v[32:35], v[192:195], v[72:75]
	v_mfma_f32_16x16x32_bf16 v[68:71], v[140:143], v[188:191], v[68:71]
	v_mfma_f32_16x16x32_bf16 v[64:67], v[32:35], v[200:203], v[64:67]
	v_mfma_f32_16x16x32_bf16 v[56:59], v[140:143], v[196:199], v[56:59]
	v_mfma_f32_16x16x32_bf16 v[48:51], v[32:35], v[212:215], v[48:51]
	v_mfma_f32_16x16x32_bf16 v[40:43], v[140:143], v[204:207], v[40:43]
	v_mfma_f32_16x16x32_bf16 v[32:35], v[32:35], v[220:223], v[4:7]
	v_mfma_f32_16x16x32_bf16 v[4:7], v[140:143], v[216:219], v[8:11]
	v_mfma_f32_16x16x32_bf16 v[68:71], v[144:147], v[192:195], v[68:71]
	v_mfma_f32_16x16x32_bf16 v[56:59], v[144:147], v[200:203], v[56:59]
	v_mfma_f32_16x16x32_bf16 v[40:43], v[144:147], v[212:215], v[40:43]
	v_mfma_f32_16x16x32_bf16 v[24:27], v[144:147], v[220:223], v[4:7]
	v_mfma_f32_16x16x32_bf16 v[4:7], v[172:175], v[188:191], v[60:63]
	v_mfma_f32_16x16x32_bf16 v[60:63], v[176:179], v[192:195], v[4:7]
	v_mfma_f32_16x16x32_bf16 v[4:7], v[180:183], v[188:191], v[52:55]
	v_mfma_f32_16x16x32_bf16 v[52:55], v[184:187], v[192:195], v[4:7]
	v_mfma_f32_16x16x32_bf16 v[4:7], v[172:175], v[196:199], v[44:47]
	v_mfma_f32_16x16x32_bf16 v[44:47], v[176:179], v[200:203], v[4:7]
	v_mfma_f32_16x16x32_bf16 v[4:7], v[180:183], v[196:199], v[36:39]
	v_mfma_f32_16x16x32_bf16 v[36:39], v[184:187], v[200:203], v[4:7]
	v_mfma_f32_16x16x32_bf16 v[4:7], v[172:175], v[204:207], v[28:31]
	v_mfma_f32_16x16x32_bf16 v[28:31], v[176:179], v[212:215], v[4:7]
	v_mfma_f32_16x16x32_bf16 v[4:7], v[180:183], v[204:207], v[20:23]
	v_mfma_f32_16x16x32_bf16 v[20:23], v[184:187], v[212:215], v[4:7]
	v_mfma_f32_16x16x32_bf16 v[4:7], v[172:175], v[216:219], v[16:19]
	v_mfma_f32_16x16x32_bf16 v[16:19], v[176:179], v[220:223], v[4:7]
	v_mfma_f32_16x16x32_bf16 v[4:7], v[180:183], v[216:219], v[12:15]
	v_mfma_f32_16x16x32_bf16 v[12:15], v[184:187], v[220:223], v[4:7]
	s_barrier
	s_setprio 0
	s_add_i32 s33, s33, 2
	s_add_u32 s22, s22, 0x1000
	s_addc_u32 s23, s23, 0
	s_add_u32 s15, s15, 0x100
	s_addc_u32 s17, s17, 0
	s_cmp_gt_u32 s33, 29
	s_cbranch_scc0 .LBB0_489

.LBB0_831:
	s_lshl_b32 s98, s100, 1
	s_add_u32 s2, s2, s100
	s_addc_u32 s3, s3, 0
	s_add_u32 s7, s22, 0x100
	s_addc_u32 s8, s23, 0
	s_mov_b32 s9, 0
	s_add_i32 s28, s9, 2
	s_add_u32 s22, s2, s100
	s_addc_u32 s23, s3, 0
	s_add_i32 s29, 0, 0x10000
	s_cmp_eq_u32 s52, s9
	s_cselect_b32 s23, s1, s23
	s_cselect_b32 s22, s0, s22
	v_add_u32_e32 v2, s29, v147
	s_cselect_b32 s35, s21, s8
	s_cselect_b32 s34, s20, s7
	s_add_i32 s9, 0, 0x14000
	ds_read_b128 v[152:155], v2
	ds_read_b128 v[156:159], v2 offset:1024
	ds_read_b128 v[160:163], v2 offset:2048
	ds_read_b128 v[168:171], v2 offset:3072
	v_add_u32_e32 v2, s9, v147
	ds_read_b128 v[172:175], v2
	ds_read_b128 v[176:179], v2 offset:1024
	ds_read_b128 v[180:183], v2 offset:2048
	ds_read_b128 v[184:187], v2 offset:3072
	s_add_i32 m0, s47, 0xc000
	ds_read_b128 v[188:191], v150
	ds_read_b128 v[192:195], v150 offset:1024
	ds_read_b128 v[196:199], v150 offset:2048
	ds_read_b128 v[200:203], v150 offset:3072
	ds_read_b128 v[204:207], v150 offset:4096
	ds_read_b128 v[210:213], v150 offset:5120
	ds_read_b128 v[214:217], v150 offset:6144
	ds_read_b128 v[218:221], v150 offset:7168
	global_load_lds_dwordx4 v140, s[2:3]
	s_add_i32 m0, s47, 0xe000
	s_nop 0
	global_load_lds_dwordx4 v142, s[2:3]
	s_waitcnt vmcnt(8)
	s_waitcnt lgkmcnt(0)
	s_setprio 1
	s_barrier
	v_mfma_f32_16x16x32_bf16 v[128:131], v[152:155], v[188:191], 0
	v_mfma_f32_16x16x32_bf16 v[124:127], v[160:163], v[188:191], 0
	v_mfma_f32_16x16x32_bf16 v[112:115], v[152:155], v[196:199], 0
	v_mfma_f32_16x16x32_bf16 v[108:111], v[160:163], v[196:199], 0
	v_mfma_f32_16x16x32_bf16 v[96:99], v[152:155], v[204:207], 0
	v_mfma_f32_16x16x32_bf16 v[92:95], v[160:163], v[204:207], 0
	v_mfma_f32_16x16x32_bf16 v[80:83], v[152:155], v[214:217], 0
	v_mfma_f32_16x16x32_bf16 v[76:79], v[160:163], v[214:217], 0
	v_mfma_f32_16x16x32_bf16 v[128:131], v[156:159], v[192:195], v[128:131]
	v_mfma_f32_16x16x32_bf16 v[124:127], v[168:171], v[192:195], v[124:127]
	v_mfma_f32_16x16x32_bf16 v[112:115], v[156:159], v[200:203], v[112:115]
	v_mfma_f32_16x16x32_bf16 v[108:111], v[168:171], v[200:203], v[108:111]
	v_mfma_f32_16x16x32_bf16 v[96:99], v[156:159], v[210:213], v[96:99]
	v_mfma_f32_16x16x32_bf16 v[92:95], v[168:171], v[210:213], v[92:95]
	v_mfma_f32_16x16x32_bf16 v[80:83], v[156:159], v[218:221], v[80:83]
	v_mfma_f32_16x16x32_bf16 v[76:79], v[168:171], v[218:221], v[76:79]
	v_mfma_f32_16x16x32_bf16 v[120:123], v[172:175], v[188:191], 0
	v_mfma_f32_16x16x32_bf16 v[116:119], v[180:183], v[188:191], 0
	v_mfma_f32_16x16x32_bf16 v[104:107], v[172:175], v[196:199], 0
	v_mfma_f32_16x16x32_bf16 v[100:103], v[180:183], v[196:199], 0
	v_mfma_f32_16x16x32_bf16 v[88:91], v[172:175], v[204:207], 0
	v_mfma_f32_16x16x32_bf16 v[84:87], v[180:183], v[204:207], 0
	v_mfma_f32_16x16x32_bf16 v[72:75], v[172:175], v[214:217], 0
	v_mfma_f32_16x16x32_bf16 v[68:71], v[180:183], v[214:217], 0
	v_mfma_f32_16x16x32_bf16 v[120:123], v[176:179], v[192:195], v[120:123]
	v_mfma_f32_16x16x32_bf16 v[116:119], v[184:187], v[192:195], v[116:119]
	v_mfma_f32_16x16x32_bf16 v[104:107], v[176:179], v[200:203], v[104:107]
	v_mfma_f32_16x16x32_bf16 v[100:103], v[184:187], v[200:203], v[100:103]
	v_mfma_f32_16x16x32_bf16 v[88:91], v[176:179], v[210:213], v[88:91]
	v_mfma_f32_16x16x32_bf16 v[84:87], v[184:187], v[210:213], v[84:87]
	v_mfma_f32_16x16x32_bf16 v[72:75], v[176:179], v[218:221], v[72:75]
	v_mfma_f32_16x16x32_bf16 v[68:71], v[184:187], v[218:221], v[68:71]
	s_barrier
	s_setprio 0
	s_add_i32 s29, s29, s26
	s_mov_b32 m0, s29
	ds_read_b128 v[188:191], v150 offset:16384
	ds_read_b128 v[192:195], v150 offset:17408
	ds_read_b128 v[196:199], v150 offset:18432
	ds_read_b128 v[200:203], v150 offset:19456
	ds_read_b128 v[204:207], v150 offset:20480
	ds_read_b128 v[210:213], v150 offset:21504
	ds_read_b128 v[214:217], v150 offset:22528
	ds_read_b128 v[218:221], v150 offset:23552
	global_load_lds_dwordx4 v136, s[34:35]
	s_add_i32 m0, s29, 0x2000
	s_add_i32 s9, s9, s26
	global_load_lds_dwordx4 v132, s[34:35]
	s_add_u32 s34, s34, s16
	s_addc_u32 s35, s35, 0
	s_mov_b32 m0, s9
	s_nop 0
	global_load_lds_dwordx4 v136, s[34:35]
	s_add_i32 m0, s9, 0x2000
	s_nop 0
	global_load_lds_dwordx4 v132, s[34:35]
	s_mov_b32 m0, s47
	s_nop 0
	global_load_lds_dwordx4 v138, s[22:23]
	s_mov_b32 m0, s48
	s_nop 0
	global_load_lds_dwordx4 v134, s[22:23]
	s_waitcnt vmcnt(8)
	s_waitcnt lgkmcnt(0)
	s_setprio 1
	s_barrier
	v_mfma_f32_16x16x32_bf16 v[64:67], v[152:155], v[188:191], 0
	v_mfma_f32_16x16x32_bf16 v[60:63], v[160:163], v[188:191], 0
	v_mfma_f32_16x16x32_bf16 v[48:51], v[152:155], v[196:199], 0
	v_mfma_f32_16x16x32_bf16 v[44:47], v[160:163], v[196:199], 0
	v_mfma_f32_16x16x32_bf16 v[32:35], v[152:155], v[204:207], 0
	v_mfma_f32_16x16x32_bf16 v[28:31], v[160:163], v[204:207], 0
	v_mfma_f32_16x16x32_bf16 v[16:19], v[152:155], v[214:217], 0
	v_mfma_f32_16x16x32_bf16 v[12:15], v[160:163], v[214:217], 0
	v_mfma_f32_16x16x32_bf16 v[64:67], v[156:159], v[192:195], v[64:67]
	v_mfma_f32_16x16x32_bf16 v[60:63], v[168:171], v[192:195], v[60:63]
	v_mfma_f32_16x16x32_bf16 v[48:51], v[156:159], v[200:203], v[48:51]
	v_mfma_f32_16x16x32_bf16 v[44:47], v[168:171], v[200:203], v[44:47]
	v_mfma_f32_16x16x32_bf16 v[32:35], v[156:159], v[210:213], v[32:35]
	v_mfma_f32_16x16x32_bf16 v[28:31], v[168:171], v[210:213], v[28:31]
	v_mfma_f32_16x16x32_bf16 v[16:19], v[156:159], v[218:221], v[16:19]
	v_mfma_f32_16x16x32_bf16 v[12:15], v[168:171], v[218:221], v[12:15]
	v_mfma_f32_16x16x32_bf16 v[56:59], v[172:175], v[188:191], 0
	v_mfma_f32_16x16x32_bf16 v[52:55], v[180:183], v[188:191], 0
	v_mfma_f32_16x16x32_bf16 v[40:43], v[172:175], v[196:199], 0
	v_mfma_f32_16x16x32_bf16 v[36:39], v[180:183], v[196:199], 0
	v_mfma_f32_16x16x32_bf16 v[24:27], v[172:175], v[204:207], 0
	v_mfma_f32_16x16x32_bf16 v[20:23], v[180:183], v[204:207], 0
	v_mfma_f32_16x16x32_bf16 v[8:11], v[172:175], v[214:217], 0
	v_mfma_f32_16x16x32_bf16 v[4:7], v[180:183], v[214:217], 0
	v_mfma_f32_16x16x32_bf16 v[56:59], v[176:179], v[192:195], v[56:59]
	v_mfma_f32_16x16x32_bf16 v[52:55], v[184:187], v[192:195], v[52:55]
	v_mfma_f32_16x16x32_bf16 v[40:43], v[176:179], v[200:203], v[40:43]
	v_mfma_f32_16x16x32_bf16 v[36:39], v[184:187], v[200:203], v[36:39]
	v_mfma_f32_16x16x32_bf16 v[24:27], v[176:179], v[210:213], v[24:27]
	v_mfma_f32_16x16x32_bf16 v[20:23], v[184:187], v[210:213], v[20:23]
	v_mfma_f32_16x16x32_bf16 v[8:11], v[176:179], v[218:221], v[8:11]
	v_mfma_f32_16x16x32_bf16 v[4:7], v[184:187], v[218:221], v[4:7]
	s_barrier
	s_setprio 0
	s_add_i32 s9, 0, 0x18000
	v_add_u32_e32 v2, s9, v147
	s_add_i32 s29, 0, 0x1c000
	ds_read_b128 v[152:155], v2
	ds_read_b128 v[156:159], v2 offset:1024
	ds_read_b128 v[160:163], v2 offset:2048
	ds_read_b128 v[168:171], v2 offset:3072
	v_add_u32_e32 v2, s29, v147
	ds_read_b128 v[172:175], v2
	ds_read_b128 v[176:179], v2 offset:1024
	ds_read_b128 v[180:183], v2 offset:2048
	ds_read_b128 v[184:187], v2 offset:3072
	s_add_u32 s22, s22, s16
	s_addc_u32 s23, s23, 0
	s_mov_b32 m0, s49
	ds_read_b128 v[188:191], v150 offset:32768
	ds_read_b128 v[192:195], v150 offset:33792
	ds_read_b128 v[196:199], v150 offset:34816
	ds_read_b128 v[200:203], v150 offset:35840
	ds_read_b128 v[204:207], v150 offset:36864
	ds_read_b128 v[210:213], v150 offset:37888
	ds_read_b128 v[214:217], v150 offset:38912
	ds_read_b128 v[218:221], v150 offset:39936
	global_load_lds_dwordx4 v138, s[22:23]
	s_mov_b32 m0, s50
	s_nop 0
	global_load_lds_dwordx4 v134, s[22:23]
	s_waitcnt vmcnt(8)
	s_waitcnt lgkmcnt(0)
	s_setprio 1
	s_barrier
	v_mfma_f32_16x16x32_bf16 v[128:131], v[152:155], v[188:191], v[128:131]
	v_mfma_f32_16x16x32_bf16 v[124:127], v[160:163], v[188:191], v[124:127]
	v_mfma_f32_16x16x32_bf16 v[112:115], v[152:155], v[196:199], v[112:115]
	v_mfma_f32_16x16x32_bf16 v[108:111], v[160:163], v[196:199], v[108:111]
	v_mfma_f32_16x16x32_bf16 v[96:99], v[152:155], v[204:207], v[96:99]
	v_mfma_f32_16x16x32_bf16 v[92:95], v[160:163], v[204:207], v[92:95]
	v_mfma_f32_16x16x32_bf16 v[80:83], v[152:155], v[214:217], v[80:83]
	v_mfma_f32_16x16x32_bf16 v[76:79], v[160:163], v[214:217], v[76:79]
	v_mfma_f32_16x16x32_bf16 v[128:131], v[156:159], v[192:195], v[128:131]
	v_mfma_f32_16x16x32_bf16 v[124:127], v[168:171], v[192:195], v[124:127]
	v_mfma_f32_16x16x32_bf16 v[112:115], v[156:159], v[200:203], v[112:115]
	v_mfma_f32_16x16x32_bf16 v[108:111], v[168:171], v[200:203], v[108:111]
	v_mfma_f32_16x16x32_bf16 v[96:99], v[156:159], v[210:213], v[96:99]
	v_mfma_f32_16x16x32_bf16 v[92:95], v[168:171], v[210:213], v[92:95]
	v_mfma_f32_16x16x32_bf16 v[80:83], v[156:159], v[218:221], v[80:83]
	v_mfma_f32_16x16x32_bf16 v[76:79], v[168:171], v[218:221], v[76:79]
	v_mfma_f32_16x16x32_bf16 v[120:123], v[172:175], v[188:191], v[120:123]
	v_mfma_f32_16x16x32_bf16 v[116:119], v[180:183], v[188:191], v[116:119]
	v_mfma_f32_16x16x32_bf16 v[104:107], v[172:175], v[196:199], v[104:107]
	v_mfma_f32_16x16x32_bf16 v[100:103], v[180:183], v[196:199], v[100:103]
	v_mfma_f32_16x16x32_bf16 v[88:91], v[172:175], v[204:207], v[88:91]
	v_mfma_f32_16x16x32_bf16 v[84:87], v[180:183], v[204:207], v[84:87]
	v_mfma_f32_16x16x32_bf16 v[72:75], v[172:175], v[214:217], v[72:75]
	v_mfma_f32_16x16x32_bf16 v[68:71], v[180:183], v[214:217], v[68:71]
	v_mfma_f32_16x16x32_bf16 v[120:123], v[176:179], v[192:195], v[120:123]
	v_mfma_f32_16x16x32_bf16 v[116:119], v[184:187], v[192:195], v[116:119]
	v_mfma_f32_16x16x32_bf16 v[104:107], v[176:179], v[200:203], v[104:107]
	v_mfma_f32_16x16x32_bf16 v[100:103], v[184:187], v[200:203], v[100:103]
	v_mfma_f32_16x16x32_bf16 v[88:91], v[176:179], v[210:213], v[88:91]
	v_mfma_f32_16x16x32_bf16 v[84:87], v[184:187], v[210:213], v[84:87]
	v_mfma_f32_16x16x32_bf16 v[72:75], v[176:179], v[218:221], v[72:75]
	v_mfma_f32_16x16x32_bf16 v[68:71], v[184:187], v[218:221], v[68:71]
	s_barrier
	s_setprio 0
	s_add_i32 s9, s9, s26
	s_mov_b32 m0, s9
	ds_read_b128 v[188:191], v150 offset:49152
	ds_read_b128 v[192:195], v150 offset:50176
	ds_read_b128 v[196:199], v150 offset:51200
	ds_read_b128 v[200:203], v150 offset:52224
	ds_read_b128 v[204:207], v150 offset:53248
	ds_read_b128 v[210:213], v150 offset:54272
	ds_read_b128 v[214:217], v150 offset:55296
	ds_read_b128 v[218:221], v150 offset:56320
	s_sub_u32 s34, s34, s16
	s_subb_u32 s35, s35, 0
	s_add_u32 s34, s34, 0x80
	s_addc_u32 s35, s35, 0
	global_load_lds_dwordx4 v136, s[34:35]
	s_add_i32 m0, s9, 0x2000
	s_add_i32 s9, s29, s26
	global_load_lds_dwordx4 v132, s[34:35]
	s_mov_b32 m0, s9
	s_nop 0
	s_add_u32 s34, s34, s16
	s_addc_u32 s35, s35, 0
	global_load_lds_dwordx4 v136, s[34:35]
	s_add_i32 m0, s9, 0x2000
	s_nop 0
	global_load_lds_dwordx4 v132, s[34:35]
	s_mov_b32 m0, s53
	s_nop 0
	s_sub_u32 s22, s22, s16
	s_subb_u32 s23, s23, 0
	s_add_u32 s22, s22, s100
	s_addc_u32 s23, s23, 0
	global_load_lds_dwordx4 v138, s[22:23]
	s_mov_b32 m0, s54
	s_nop 0
	global_load_lds_dwordx4 v134, s[22:23]
	s_waitcnt vmcnt(8)
	s_waitcnt lgkmcnt(0)
	s_setprio 1
	s_barrier
	v_mfma_f32_16x16x32_bf16 v[64:67], v[152:155], v[188:191], v[64:67]
	v_mfma_f32_16x16x32_bf16 v[60:63], v[160:163], v[188:191], v[60:63]
	v_mfma_f32_16x16x32_bf16 v[48:51], v[152:155], v[196:199], v[48:51]
	v_mfma_f32_16x16x32_bf16 v[44:47], v[160:163], v[196:199], v[44:47]
	v_mfma_f32_16x16x32_bf16 v[32:35], v[152:155], v[204:207], v[32:35]
	v_mfma_f32_16x16x32_bf16 v[28:31], v[160:163], v[204:207], v[28:31]
	v_mfma_f32_16x16x32_bf16 v[16:19], v[152:155], v[214:217], v[16:19]
	v_mfma_f32_16x16x32_bf16 v[12:15], v[160:163], v[214:217], v[12:15]
	v_mfma_f32_16x16x32_bf16 v[64:67], v[156:159], v[192:195], v[64:67]
	v_mfma_f32_16x16x32_bf16 v[60:63], v[168:171], v[192:195], v[60:63]
	v_mfma_f32_16x16x32_bf16 v[48:51], v[156:159], v[200:203], v[48:51]
	v_mfma_f32_16x16x32_bf16 v[44:47], v[168:171], v[200:203], v[44:47]
	v_mfma_f32_16x16x32_bf16 v[32:35], v[156:159], v[210:213], v[32:35]
	v_mfma_f32_16x16x32_bf16 v[28:31], v[168:171], v[210:213], v[28:31]
	v_mfma_f32_16x16x32_bf16 v[16:19], v[156:159], v[218:221], v[16:19]
	v_mfma_f32_16x16x32_bf16 v[12:15], v[168:171], v[218:221], v[12:15]
	v_mfma_f32_16x16x32_bf16 v[56:59], v[172:175], v[188:191], v[56:59]
	v_mfma_f32_16x16x32_bf16 v[52:55], v[180:183], v[188:191], v[52:55]
	v_mfma_f32_16x16x32_bf16 v[40:43], v[172:175], v[196:199], v[40:43]
	v_mfma_f32_16x16x32_bf16 v[36:39], v[180:183], v[196:199], v[36:39]
	v_mfma_f32_16x16x32_bf16 v[24:27], v[172:175], v[204:207], v[24:27]
	v_mfma_f32_16x16x32_bf16 v[20:23], v[180:183], v[204:207], v[20:23]
	v_mfma_f32_16x16x32_bf16 v[8:11], v[172:175], v[214:217], v[8:11]
	v_mfma_f32_16x16x32_bf16 v[4:7], v[180:183], v[214:217], v[4:7]
	v_mfma_f32_16x16x32_bf16 v[56:59], v[176:179], v[192:195], v[56:59]
	v_mfma_f32_16x16x32_bf16 v[52:55], v[184:187], v[192:195], v[52:55]
	v_mfma_f32_16x16x32_bf16 v[40:43], v[176:179], v[200:203], v[40:43]
	v_mfma_f32_16x16x32_bf16 v[36:39], v[184:187], v[200:203], v[36:39]
	v_mfma_f32_16x16x32_bf16 v[24:27], v[176:179], v[210:213], v[24:27]
	v_mfma_f32_16x16x32_bf16 v[20:23], v[184:187], v[210:213], v[20:23]
	v_mfma_f32_16x16x32_bf16 v[8:11], v[176:179], v[218:221], v[8:11]
	v_mfma_f32_16x16x32_bf16 v[4:7], v[184:187], v[218:221], v[4:7]
	s_barrier
	s_setprio 0
	s_add_u32 s2, s2, s98
	s_addc_u32 s3, s3, 0
	s_add_u32 s7, s7, 0x100
	s_addc_u32 s8, s8, 0
	s_cmp_ge_u32 s28, s51
	s_mov_b32 s9, s28
	s_cbranch_scc0 .LBB0_832
	s_branch .Lpeel_done_832
.LBB0_832:
	s_add_i32 s28, s9, 2
	s_add_u32 s22, s2, s100
	s_addc_u32 s23, s3, 0
	s_add_i32 s29, 0, 0x10000
	s_cmp_eq_u32 s52, s9
	s_cselect_b32 s23, s1, s23
	s_cselect_b32 s22, s0, s22
	v_add_u32_e32 v2, s29, v147
	s_cselect_b32 s35, s21, s8
	s_cselect_b32 s34, s20, s7
	s_add_i32 s9, 0, 0x14000
	ds_read_b128 v[152:155], v2
	ds_read_b128 v[156:159], v2 offset:1024
	ds_read_b128 v[160:163], v2 offset:2048
	ds_read_b128 v[168:171], v2 offset:3072
	v_add_u32_e32 v2, s9, v147
	ds_read_b128 v[172:175], v2
	ds_read_b128 v[176:179], v2 offset:1024
	ds_read_b128 v[180:183], v2 offset:2048
	ds_read_b128 v[184:187], v2 offset:3072
	s_add_i32 m0, s47, 0xc000
	ds_read_b128 v[188:191], v150
	ds_read_b128 v[192:195], v150 offset:1024
	ds_read_b128 v[196:199], v150 offset:2048
	ds_read_b128 v[200:203], v150 offset:3072
	ds_read_b128 v[204:207], v150 offset:4096
	ds_read_b128 v[210:213], v150 offset:5120
	ds_read_b128 v[214:217], v150 offset:6144
	ds_read_b128 v[218:221], v150 offset:7168
	global_load_lds_dwordx4 v140, s[2:3]
	s_add_i32 m0, s47, 0xe000
	s_nop 0
	global_load_lds_dwordx4 v142, s[2:3]
	s_waitcnt vmcnt(8)
	s_waitcnt lgkmcnt(0)
	s_setprio 1
	s_barrier
	v_mfma_f32_16x16x32_bf16 v[128:131], v[152:155], v[188:191], v[128:131]
	v_mfma_f32_16x16x32_bf16 v[124:127], v[160:163], v[188:191], v[124:127]
	v_mfma_f32_16x16x32_bf16 v[112:115], v[152:155], v[196:199], v[112:115]
	v_mfma_f32_16x16x32_bf16 v[108:111], v[160:163], v[196:199], v[108:111]
	v_mfma_f32_16x16x32_bf16 v[96:99], v[152:155], v[204:207], v[96:99]
	v_mfma_f32_16x16x32_bf16 v[92:95], v[160:163], v[204:207], v[92:95]
	v_mfma_f32_16x16x32_bf16 v[80:83], v[152:155], v[214:217], v[80:83]
	v_mfma_f32_16x16x32_bf16 v[76:79], v[160:163], v[214:217], v[76:79]
	v_mfma_f32_16x16x32_bf16 v[128:131], v[156:159], v[192:195], v[128:131]
	v_mfma_f32_16x16x32_bf16 v[124:127], v[168:171], v[192:195], v[124:127]
	v_mfma_f32_16x16x32_bf16 v[112:115], v[156:159], v[200:203], v[112:115]
	v_mfma_f32_16x16x32_bf16 v[108:111], v[168:171], v[200:203], v[108:111]
	v_mfma_f32_16x16x32_bf16 v[96:99], v[156:159], v[210:213], v[96:99]
	v_mfma_f32_16x16x32_bf16 v[92:95], v[168:171], v[210:213], v[92:95]
	v_mfma_f32_16x16x32_bf16 v[80:83], v[156:159], v[218:221], v[80:83]
	v_mfma_f32_16x16x32_bf16 v[76:79], v[168:171], v[218:221], v[76:79]
	v_mfma_f32_16x16x32_bf16 v[120:123], v[172:175], v[188:191], v[120:123]
	v_mfma_f32_16x16x32_bf16 v[116:119], v[180:183], v[188:191], v[116:119]
	v_mfma_f32_16x16x32_bf16 v[104:107], v[172:175], v[196:199], v[104:107]
	v_mfma_f32_16x16x32_bf16 v[100:103], v[180:183], v[196:199], v[100:103]
	v_mfma_f32_16x16x32_bf16 v[88:91], v[172:175], v[204:207], v[88:91]
	v_mfma_f32_16x16x32_bf16 v[84:87], v[180:183], v[204:207], v[84:87]
	v_mfma_f32_16x16x32_bf16 v[72:75], v[172:175], v[214:217], v[72:75]
	v_mfma_f32_16x16x32_bf16 v[68:71], v[180:183], v[214:217], v[68:71]
	v_mfma_f32_16x16x32_bf16 v[120:123], v[176:179], v[192:195], v[120:123]
	v_mfma_f32_16x16x32_bf16 v[116:119], v[184:187], v[192:195], v[116:119]
	v_mfma_f32_16x16x32_bf16 v[104:107], v[176:179], v[200:203], v[104:107]
	v_mfma_f32_16x16x32_bf16 v[100:103], v[184:187], v[200:203], v[100:103]
	v_mfma_f32_16x16x32_bf16 v[88:91], v[176:179], v[210:213], v[88:91]
	v_mfma_f32_16x16x32_bf16 v[84:87], v[184:187], v[210:213], v[84:87]
	v_mfma_f32_16x16x32_bf16 v[72:75], v[176:179], v[218:221], v[72:75]
	v_mfma_f32_16x16x32_bf16 v[68:71], v[184:187], v[218:221], v[68:71]
	s_barrier
	s_setprio 0
	s_add_i32 s29, s29, s26
	s_mov_b32 m0, s29
	ds_read_b128 v[188:191], v150 offset:16384
	ds_read_b128 v[192:195], v150 offset:17408
	ds_read_b128 v[196:199], v150 offset:18432
	ds_read_b128 v[200:203], v150 offset:19456
	ds_read_b128 v[204:207], v150 offset:20480
	ds_read_b128 v[210:213], v150 offset:21504
	ds_read_b128 v[214:217], v150 offset:22528
	ds_read_b128 v[218:221], v150 offset:23552
	global_load_lds_dwordx4 v136, s[34:35]
	s_add_i32 m0, s29, 0x2000
	s_add_i32 s9, s9, s26
	global_load_lds_dwordx4 v132, s[34:35]
	s_add_u32 s34, s34, s16
	s_addc_u32 s35, s35, 0
	s_mov_b32 m0, s9
	s_nop 0
	global_load_lds_dwordx4 v136, s[34:35]
	s_add_i32 m0, s9, 0x2000
	s_nop 0
	global_load_lds_dwordx4 v132, s[34:35]
	s_mov_b32 m0, s47
	s_nop 0
	global_load_lds_dwordx4 v138, s[22:23]
	s_mov_b32 m0, s48
	s_nop 0
	global_load_lds_dwordx4 v134, s[22:23]
	s_waitcnt vmcnt(8)
	s_waitcnt lgkmcnt(0)
	s_setprio 1
	s_barrier
	v_mfma_f32_16x16x32_bf16 v[64:67], v[152:155], v[188:191], v[64:67]
	v_mfma_f32_16x16x32_bf16 v[60:63], v[160:163], v[188:191], v[60:63]
	v_mfma_f32_16x16x32_bf16 v[48:51], v[152:155], v[196:199], v[48:51]
	v_mfma_f32_16x16x32_bf16 v[44:47], v[160:163], v[196:199], v[44:47]
	v_mfma_f32_16x16x32_bf16 v[32:35], v[152:155], v[204:207], v[32:35]
	v_mfma_f32_16x16x32_bf16 v[28:31], v[160:163], v[204:207], v[28:31]
	v_mfma_f32_16x16x32_bf16 v[16:19], v[152:155], v[214:217], v[16:19]
	v_mfma_f32_16x16x32_bf16 v[12:15], v[160:163], v[214:217], v[12:15]
	v_mfma_f32_16x16x32_bf16 v[64:67], v[156:159], v[192:195], v[64:67]
	v_mfma_f32_16x16x32_bf16 v[60:63], v[168:171], v[192:195], v[60:63]
	v_mfma_f32_16x16x32_bf16 v[48:51], v[156:159], v[200:203], v[48:51]
	v_mfma_f32_16x16x32_bf16 v[44:47], v[168:171], v[200:203], v[44:47]
	v_mfma_f32_16x16x32_bf16 v[32:35], v[156:159], v[210:213], v[32:35]
	v_mfma_f32_16x16x32_bf16 v[28:31], v[168:171], v[210:213], v[28:31]
	v_mfma_f32_16x16x32_bf16 v[16:19], v[156:159], v[218:221], v[16:19]
	v_mfma_f32_16x16x32_bf16 v[12:15], v[168:171], v[218:221], v[12:15]
	v_mfma_f32_16x16x32_bf16 v[56:59], v[172:175], v[188:191], v[56:59]
	v_mfma_f32_16x16x32_bf16 v[52:55], v[180:183], v[188:191], v[52:55]
	v_mfma_f32_16x16x32_bf16 v[40:43], v[172:175], v[196:199], v[40:43]
	v_mfma_f32_16x16x32_bf16 v[36:39], v[180:183], v[196:199], v[36:39]
	v_mfma_f32_16x16x32_bf16 v[24:27], v[172:175], v[204:207], v[24:27]
	v_mfma_f32_16x16x32_bf16 v[20:23], v[180:183], v[204:207], v[20:23]
	v_mfma_f32_16x16x32_bf16 v[8:11], v[172:175], v[214:217], v[8:11]
	v_mfma_f32_16x16x32_bf16 v[4:7], v[180:183], v[214:217], v[4:7]
	v_mfma_f32_16x16x32_bf16 v[56:59], v[176:179], v[192:195], v[56:59]
	v_mfma_f32_16x16x32_bf16 v[52:55], v[184:187], v[192:195], v[52:55]
	v_mfma_f32_16x16x32_bf16 v[40:43], v[176:179], v[200:203], v[40:43]
	v_mfma_f32_16x16x32_bf16 v[36:39], v[184:187], v[200:203], v[36:39]
	v_mfma_f32_16x16x32_bf16 v[24:27], v[176:179], v[210:213], v[24:27]
	v_mfma_f32_16x16x32_bf16 v[20:23], v[184:187], v[210:213], v[20:23]
	v_mfma_f32_16x16x32_bf16 v[8:11], v[176:179], v[218:221], v[8:11]
	v_mfma_f32_16x16x32_bf16 v[4:7], v[184:187], v[218:221], v[4:7]
	s_barrier
	s_setprio 0
	s_add_i32 s9, 0, 0x18000
	v_add_u32_e32 v2, s9, v147
	s_add_i32 s29, 0, 0x1c000
	ds_read_b128 v[152:155], v2
	ds_read_b128 v[156:159], v2 offset:1024
	ds_read_b128 v[160:163], v2 offset:2048
	ds_read_b128 v[168:171], v2 offset:3072
	v_add_u32_e32 v2, s29, v147
	ds_read_b128 v[172:175], v2
	ds_read_b128 v[176:179], v2 offset:1024
	ds_read_b128 v[180:183], v2 offset:2048
	ds_read_b128 v[184:187], v2 offset:3072
	s_add_u32 s22, s22, s16
	s_addc_u32 s23, s23, 0
	s_mov_b32 m0, s49
	ds_read_b128 v[188:191], v150 offset:32768
	ds_read_b128 v[192:195], v150 offset:33792
	ds_read_b128 v[196:199], v150 offset:34816
	ds_read_b128 v[200:203], v150 offset:35840
	ds_read_b128 v[204:207], v150 offset:36864
	ds_read_b128 v[210:213], v150 offset:37888
	ds_read_b128 v[214:217], v150 offset:38912
	ds_read_b128 v[218:221], v150 offset:39936
	global_load_lds_dwordx4 v138, s[22:23]
	s_mov_b32 m0, s50
	s_nop 0
	global_load_lds_dwordx4 v134, s[22:23]
	s_waitcnt vmcnt(8)
	s_waitcnt lgkmcnt(0)
	s_setprio 1
	s_barrier
	v_mfma_f32_16x16x32_bf16 v[128:131], v[152:155], v[188:191], v[128:131]
	v_mfma_f32_16x16x32_bf16 v[124:127], v[160:163], v[188:191], v[124:127]
	v_mfma_f32_16x16x32_bf16 v[112:115], v[152:155], v[196:199], v[112:115]
	v_mfma_f32_16x16x32_bf16 v[108:111], v[160:163], v[196:199], v[108:111]
	v_mfma_f32_16x16x32_bf16 v[96:99], v[152:155], v[204:207], v[96:99]
	v_mfma_f32_16x16x32_bf16 v[92:95], v[160:163], v[204:207], v[92:95]
	v_mfma_f32_16x16x32_bf16 v[80:83], v[152:155], v[214:217], v[80:83]
	v_mfma_f32_16x16x32_bf16 v[76:79], v[160:163], v[214:217], v[76:79]
	v_mfma_f32_16x16x32_bf16 v[128:131], v[156:159], v[192:195], v[128:131]
	v_mfma_f32_16x16x32_bf16 v[124:127], v[168:171], v[192:195], v[124:127]
	v_mfma_f32_16x16x32_bf16 v[112:115], v[156:159], v[200:203], v[112:115]
	v_mfma_f32_16x16x32_bf16 v[108:111], v[168:171], v[200:203], v[108:111]
	v_mfma_f32_16x16x32_bf16 v[96:99], v[156:159], v[210:213], v[96:99]
	v_mfma_f32_16x16x32_bf16 v[92:95], v[168:171], v[210:213], v[92:95]
	v_mfma_f32_16x16x32_bf16 v[80:83], v[156:159], v[218:221], v[80:83]
	v_mfma_f32_16x16x32_bf16 v[76:79], v[168:171], v[218:221], v[76:79]
	v_mfma_f32_16x16x32_bf16 v[120:123], v[172:175], v[188:191], v[120:123]
	v_mfma_f32_16x16x32_bf16 v[116:119], v[180:183], v[188:191], v[116:119]
	v_mfma_f32_16x16x32_bf16 v[104:107], v[172:175], v[196:199], v[104:107]
	v_mfma_f32_16x16x32_bf16 v[100:103], v[180:183], v[196:199], v[100:103]
	v_mfma_f32_16x16x32_bf16 v[88:91], v[172:175], v[204:207], v[88:91]
	v_mfma_f32_16x16x32_bf16 v[84:87], v[180:183], v[204:207], v[84:87]
	v_mfma_f32_16x16x32_bf16 v[72:75], v[172:175], v[214:217], v[72:75]
	v_mfma_f32_16x16x32_bf16 v[68:71], v[180:183], v[214:217], v[68:71]
	v_mfma_f32_16x16x32_bf16 v[120:123], v[176:179], v[192:195], v[120:123]
	v_mfma_f32_16x16x32_bf16 v[116:119], v[184:187], v[192:195], v[116:119]
	v_mfma_f32_16x16x32_bf16 v[104:107], v[176:179], v[200:203], v[104:107]
	v_mfma_f32_16x16x32_bf16 v[100:103], v[184:187], v[200:203], v[100:103]
	v_mfma_f32_16x16x32_bf16 v[88:91], v[176:179], v[210:213], v[88:91]
	v_mfma_f32_16x16x32_bf16 v[84:87], v[184:187], v[210:213], v[84:87]
	v_mfma_f32_16x16x32_bf16 v[72:75], v[176:179], v[218:221], v[72:75]
	v_mfma_f32_16x16x32_bf16 v[68:71], v[184:187], v[218:221], v[68:71]
	s_barrier
	s_setprio 0
	s_add_i32 s9, s9, s26
	s_mov_b32 m0, s9
	ds_read_b128 v[188:191], v150 offset:49152
	ds_read_b128 v[192:195], v150 offset:50176
	ds_read_b128 v[196:199], v150 offset:51200
	ds_read_b128 v[200:203], v150 offset:52224
	ds_read_b128 v[204:207], v150 offset:53248
	ds_read_b128 v[210:213], v150 offset:54272
	ds_read_b128 v[214:217], v150 offset:55296
	ds_read_b128 v[218:221], v150 offset:56320
	s_sub_u32 s34, s34, s16
	s_subb_u32 s35, s35, 0
	s_add_u32 s34, s34, 0x80
	s_addc_u32 s35, s35, 0
	global_load_lds_dwordx4 v136, s[34:35]
	s_add_i32 m0, s9, 0x2000
	s_add_i32 s9, s29, s26
	global_load_lds_dwordx4 v132, s[34:35]
	s_mov_b32 m0, s9
	s_nop 0
	s_add_u32 s34, s34, s16
	s_addc_u32 s35, s35, 0
	global_load_lds_dwordx4 v136, s[34:35]
	s_add_i32 m0, s9, 0x2000
	s_nop 0
	global_load_lds_dwordx4 v132, s[34:35]
	s_mov_b32 m0, s53
	s_nop 0
	s_sub_u32 s22, s22, s16
	s_subb_u32 s23, s23, 0
	s_add_u32 s22, s22, s100
	s_addc_u32 s23, s23, 0
	global_load_lds_dwordx4 v138, s[22:23]
	s_mov_b32 m0, s54
	s_nop 0
	global_load_lds_dwordx4 v134, s[22:23]
	s_waitcnt vmcnt(8)
	s_waitcnt lgkmcnt(0)
	s_setprio 1
	s_barrier
	v_mfma_f32_16x16x32_bf16 v[64:67], v[152:155], v[188:191], v[64:67]
	v_mfma_f32_16x16x32_bf16 v[60:63], v[160:163], v[188:191], v[60:63]
	v_mfma_f32_16x16x32_bf16 v[48:51], v[152:155], v[196:199], v[48:51]
	v_mfma_f32_16x16x32_bf16 v[44:47], v[160:163], v[196:199], v[44:47]
	v_mfma_f32_16x16x32_bf16 v[32:35], v[152:155], v[204:207], v[32:35]
	v_mfma_f32_16x16x32_bf16 v[28:31], v[160:163], v[204:207], v[28:31]
	v_mfma_f32_16x16x32_bf16 v[16:19], v[152:155], v[214:217], v[16:19]
	v_mfma_f32_16x16x32_bf16 v[12:15], v[160:163], v[214:217], v[12:15]
	v_mfma_f32_16x16x32_bf16 v[64:67], v[156:159], v[192:195], v[64:67]
	v_mfma_f32_16x16x32_bf16 v[60:63], v[168:171], v[192:195], v[60:63]
	v_mfma_f32_16x16x32_bf16 v[48:51], v[156:159], v[200:203], v[48:51]
	v_mfma_f32_16x16x32_bf16 v[44:47], v[168:171], v[200:203], v[44:47]
	v_mfma_f32_16x16x32_bf16 v[32:35], v[156:159], v[210:213], v[32:35]
	v_mfma_f32_16x16x32_bf16 v[28:31], v[168:171], v[210:213], v[28:31]
	v_mfma_f32_16x16x32_bf16 v[16:19], v[156:159], v[218:221], v[16:19]
	v_mfma_f32_16x16x32_bf16 v[12:15], v[168:171], v[218:221], v[12:15]
	v_mfma_f32_16x16x32_bf16 v[56:59], v[172:175], v[188:191], v[56:59]
	v_mfma_f32_16x16x32_bf16 v[52:55], v[180:183], v[188:191], v[52:55]
	v_mfma_f32_16x16x32_bf16 v[40:43], v[172:175], v[196:199], v[40:43]
	v_mfma_f32_16x16x32_bf16 v[36:39], v[180:183], v[196:199], v[36:39]
	v_mfma_f32_16x16x32_bf16 v[24:27], v[172:175], v[204:207], v[24:27]
	v_mfma_f32_16x16x32_bf16 v[20:23], v[180:183], v[204:207], v[20:23]
	v_mfma_f32_16x16x32_bf16 v[8:11], v[172:175], v[214:217], v[8:11]
	v_mfma_f32_16x16x32_bf16 v[4:7], v[180:183], v[214:217], v[4:7]
	v_mfma_f32_16x16x32_bf16 v[56:59], v[176:179], v[192:195], v[56:59]
	v_mfma_f32_16x16x32_bf16 v[52:55], v[184:187], v[192:195], v[52:55]
	v_mfma_f32_16x16x32_bf16 v[40:43], v[176:179], v[200:203], v[40:43]
	v_mfma_f32_16x16x32_bf16 v[36:39], v[184:187], v[200:203], v[36:39]
	v_mfma_f32_16x16x32_bf16 v[24:27], v[176:179], v[210:213], v[24:27]
	v_mfma_f32_16x16x32_bf16 v[20:23], v[184:187], v[210:213], v[20:23]
	v_mfma_f32_16x16x32_bf16 v[8:11], v[176:179], v[218:221], v[8:11]
	v_mfma_f32_16x16x32_bf16 v[4:7], v[184:187], v[218:221], v[4:7]
	s_barrier
	s_setprio 0
	s_add_u32 s2, s2, s98
	s_addc_u32 s3, s3, 0
	s_add_u32 s7, s7, 0x100
	s_addc_u32 s8, s8, 0
	s_cmp_ge_u32 s28, s51
	s_mov_b32 s9, s28
	s_cbranch_scc0 .LBB0_832
